# wbconv
# speedup vs baseline: 1.0079x; 1.0079x over previous
; __device__ __forceinline__ void mixer_phase(const Params& p, char* shm) {
;     ...
;     if (h != h_loaded)
; #pragma unroll
;     for (int i = 0; i < 8; ++i) {
;       int q = tid + i * 512;
;       int t = q >> 5, s4 = (q & 31) * 4;
;       float4 v = *(const float4*)(w + t * 128 + s4);
;       if (s4 + 0 > t) v.x = 0.f;
;       if (s4 + 1 > t) v.y = 0.f;
;       if (s4 + 2 > t) v.z = 0.f;
;       if (s4 + 3 > t) v.w = 0.f;
;       *(uint2*)(ldsW + t * 136 + s4) = make_uint2(pack2(v.x, v.y), pack2(v.z, v.w));
;     }
.LBB0_426:
	s_mov_b32 s3, s79
	s_and_b32 s79, s2, 7
	s_cmp_eq_u32 s79, s3
	s_cbranch_scc1 .LBB0_428
	s_lshl_b32 s8, s79, 16
	v_lshl_add_u64 v[0:1], v[52:53], 0, s[8:9]
	v_lshl_add_u64 v[152:153], v[36:37], 2, v[0:1]
	global_load_dwordx4 v[120:123], v[152:153], off
	v_lshl_add_u64 v[152:153], v[38:39], 2, v[0:1]
	global_load_dwordx4 v[124:127], v[152:153], off
	v_lshl_add_u64 v[152:153], v[40:41], 2, v[0:1]
	global_load_dwordx4 v[128:131], v[152:153], off
	v_lshl_add_u64 v[152:153], v[42:43], 2, v[0:1]
	global_load_dwordx4 v[132:135], v[152:153], off
	v_lshl_add_u64 v[152:153], v[44:45], 2, v[0:1]
	global_load_dwordx4 v[136:139], v[152:153], off
	v_lshl_add_u64 v[152:153], v[46:47], 2, v[0:1]
	global_load_dwordx4 v[140:143], v[152:153], off
	v_lshl_add_u64 v[152:153], v[48:49], 2, v[0:1]
	global_load_dwordx4 v[144:147], v[152:153], off
	v_lshl_add_u64 v[152:153], v[50:51], 2, v[0:1]
	global_load_dwordx4 v[148:151], v[152:153], off
	v_readlane_b32 s68, v244, 10
	v_readlane_b32 s69, v244, 11
	s_waitcnt vmcnt(7)
	v_mov_b32_e32 v2, v120
	v_mov_b32_e32 v3, v121
	v_mov_b32_e32 v4, v122
	v_mov_b32_e32 v5, v123
	s_nop 0
	v_cndmask_b32_e64 v3, 0, v3, s[68:69]
	v_readlane_b32 s68, v244, 12
	v_readlane_b32 s69, v244, 13
	s_nop 1
	v_cndmask_b32_e64 v2, v2, 0, s[68:69]
	v_readlane_b32 s68, v244, 16
	v_cvt_pk_bf16_f32 v2, v2, v3
	v_cvt_pk_bf16_f32 v3, v4, v5
	v_readlane_b32 s69, v244, 17
	s_nop 1
	v_cndmask_b32_e64 v4, v3, 0, s[68:69]
	v_readlane_b32 s68, v244, 14
	v_lshrrev_b32_e32 v3, 16, v3
	v_readlane_b32 s69, v244, 15
	s_nop 1
	v_cndmask_b32_e64 v3, v3, 0, s[68:69]
	v_perm_b32 v3, v3, v4, s81
	ds_write_b64 v66, v[2:3]
	v_readlane_b32 s68, v244, 18
	v_readlane_b32 s69, v244, 19
	s_waitcnt vmcnt(6)
	v_mov_b32_e32 v2, v124
	v_mov_b32_e32 v3, v125
	v_mov_b32_e32 v4, v126
	v_mov_b32_e32 v5, v127
	s_nop 0
	v_cndmask_b32_e64 v2, v2, 0, s[68:69]
	v_readlane_b32 s68, v244, 20
	v_readlane_b32 s69, v244, 21
	s_nop 1
	v_cndmask_b32_e64 v3, 0, v3, s[68:69]
	v_readlane_b32 s68, v244, 24
	v_cvt_pk_bf16_f32 v2, v2, v3
	v_cvt_pk_bf16_f32 v3, v4, v5
	v_readlane_b32 s69, v244, 25
	s_nop 1
	v_cndmask_b32_e64 v4, v3, 0, s[68:69]
	v_readlane_b32 s68, v244, 22
	v_lshrrev_b32_e32 v3, 16, v3
	v_readlane_b32 s69, v244, 23
	s_nop 1
	v_cndmask_b32_e64 v3, v3, 0, s[68:69]
	v_perm_b32 v3, v3, v4, s81
	ds_write_b64 v67, v[2:3]
	v_readlane_b32 s68, v244, 26
	v_readlane_b32 s69, v244, 27
	s_waitcnt vmcnt(5)
	v_mov_b32_e32 v2, v128
	v_mov_b32_e32 v3, v129
	v_mov_b32_e32 v4, v130
	v_mov_b32_e32 v5, v131
	v_cndmask_b32_e64 v3, 0, v3, s[4:5]
	v_cndmask_b32_e64 v2, v2, 0, s[68:69]
	v_cvt_pk_bf16_f32 v2, v2, v3
	v_cvt_pk_bf16_f32 v3, v4, v5
	v_cndmask_b32_e64 v4, v3, 0, s[0:1]
	v_lshrrev_b32_e32 v3, 16, v3
	v_cndmask_b32_e64 v3, v3, 0, s[96:97]
	v_perm_b32 v3, v3, v4, s81
	ds_write_b64 v66, v[2:3] offset:8704
	s_waitcnt vmcnt(4)
	v_mov_b32_e32 v2, v132
	v_mov_b32_e32 v3, v133
	v_mov_b32_e32 v4, v134
	v_mov_b32_e32 v5, v135
	v_cndmask_b32_e64 v2, v2, 0, s[24:25]
	v_cndmask_b32_e64 v3, 0, v3, s[26:27]
	v_cvt_pk_bf16_f32 v2, v2, v3
	v_cvt_pk_bf16_f32 v3, v4, v5
	v_cndmask_b32_e64 v4, v3, 0, s[30:31]
	v_lshrrev_b32_e32 v3, 16, v3
	v_cndmask_b32_e64 v3, v3, 0, s[28:29]
	v_perm_b32 v3, v3, v4, s81
	ds_write_b64 v68, v[2:3]
	s_waitcnt vmcnt(3)
	v_mov_b32_e32 v2, v136
	v_mov_b32_e32 v3, v137
	v_mov_b32_e32 v4, v138
	v_mov_b32_e32 v5, v139
	v_cndmask_b32_e64 v2, v2, 0, s[34:35]
	v_cndmask_b32_e64 v3, 0, v3, s[36:37]
	v_cvt_pk_bf16_f32 v2, v2, v3
	v_cvt_pk_bf16_f32 v3, v4, v5
	v_cndmask_b32_e64 v4, v3, 0, s[40:41]
	v_lshrrev_b32_e32 v3, 16, v3
	v_cndmask_b32_e64 v3, v3, 0, s[38:39]
	v_perm_b32 v3, v3, v4, s81
	ds_write_b64 v66, v[2:3] offset:17408
	s_waitcnt vmcnt(2)
	v_mov_b32_e32 v2, v140
	v_mov_b32_e32 v3, v141
	v_mov_b32_e32 v4, v142
	v_mov_b32_e32 v5, v143
	v_cndmask_b32_e64 v2, v2, 0, s[42:43]
	v_cndmask_b32_e64 v3, 0, v3, s[48:49]
	v_cvt_pk_bf16_f32 v2, v2, v3
	v_cvt_pk_bf16_f32 v3, v4, v5
	v_cndmask_b32_e64 v4, v3, 0, vcc
	v_lshrrev_b32_e32 v3, 16, v3
	v_cndmask_b32_e64 v3, v3, 0, s[50:51]
	v_perm_b32 v3, v3, v4, s81
	ds_write_b64 v69, v[2:3]
	s_waitcnt vmcnt(1)
	v_mov_b32_e32 v2, v144
	v_mov_b32_e32 v3, v145
	v_mov_b32_e32 v4, v146
	v_mov_b32_e32 v5, v147
	v_cndmask_b32_e64 v2, v2, 0, s[66:67]
	v_cndmask_b32_e64 v3, 0, v3, s[52:53]
	v_cvt_pk_bf16_f32 v2, v2, v3
	v_cvt_pk_bf16_f32 v3, v4, v5
	v_cndmask_b32_e64 v4, v3, 0, s[56:57]
	v_lshrrev_b32_e32 v3, 16, v3
	v_cndmask_b32_e64 v3, v3, 0, s[54:55]
	v_perm_b32 v3, v3, v4, s81
	ds_write_b64 v66, v[2:3] offset:26112
	s_waitcnt vmcnt(0)
	v_mov_b32_e32 v0, v148
	v_mov_b32_e32 v1, v149
	v_mov_b32_e32 v2, v150
	v_mov_b32_e32 v3, v151
	v_cndmask_b32_e64 v0, v0, 0, s[58:59]
	v_cndmask_b32_e64 v1, 0, v1, s[60:61]
	v_cvt_pk_bf16_f32 v0, v0, v1
	v_cvt_pk_bf16_f32 v1, v2, v3
	v_cndmask_b32_e64 v2, v1, 0, s[64:65]
	v_lshrrev_b32_e32 v1, 16, v1
	v_cndmask_b32_e64 v1, v1, 0, s[62:63]
	v_perm_b32 v1, v1, v2, s81
	ds_write_b64 v70, v[0:1]

; __device__ __forceinline__ float bf_lo(u32 v) { return __uint_as_float(v << 16); }
; __device__ __forceinline__ float bf_hi(u32 v) { return __uint_as_float(v & 0xFFFF0000u); }
; __device__ __forceinline__ void mixer_phase(const Params& p, char* shm) {
;     ...
;       for (int r = 0; r < 16; ++r) {
;         const u16* zr = z + (size_t)(row0 + r) * DIN;
;         uint4 gb = *(const uint4*)(zr + 2048 + c0);
;         uint4 gc = *(const uint4*)(zr + 3072 + c0);
;         uint4 xt = *(const uint4*)(zr + 4096 + c0);
;         float hh[8], gbf[8], y[8];
;         hh[0] = bf_lo(gc.x) * bf_lo(xt.x); hh[1] = bf_hi(gc.x) * bf_hi(xt.x);
;         hh[2] = bf_lo(gc.y) * bf_lo(xt.y); hh[3] = bf_hi(gc.y) * bf_hi(xt.y);
;         hh[4] = bf_lo(gc.z) * bf_lo(xt.z); hh[5] = bf_hi(gc.z) * bf_hi(xt.z);
;         hh[6] = bf_lo(gc.w) * bf_lo(xt.w); hh[7] = bf_hi(gc.w) * bf_hi(xt.w);
;         gbf[0] = bf_lo(gb.x); gbf[1] = bf_hi(gb.x); gbf[2] = bf_lo(gb.y); gbf[3] = bf_hi(gb.y);
;         gbf[4] = bf_lo(gb.z); gbf[5] = bf_hi(gb.z); gbf[6] = bf_lo(gb.w); gbf[7] = bf_hi(gb.w);
; #pragma unroll
;         for (int e = 0; e < 8; ++e) {
;           y[e] = gbf[e] * (w0[e] * h2[e] + w1[e] * h1[e] + w2[e] * hh[e]);
;           h2[e] = h1[e]; h1[e] = hh[e];
;         }
;         uint4 o;
;         o.x = pack2(y[0], y[1]); o.y = pack2(y[2], y[3]); o.z = pack2(y[4], y[5]); o.w = pack2(y[6], y[7]);
;         *(uint4*)((char*)ymix + tl_off(row0 + r, DA + c0, DM >> 6)) = o;
;       }
.LBB0_436:
	v_lshl_add_u64 v[112:113], v[36:37], 0, s[10:11]
	v_add_co_u32_e32 v114, vcc, s26, v112
	s_nop 1
	v_addc_co_u32_e32 v115, vcc, 0, v113, vcc
	v_add_co_u32_e32 v116, vcc, s27, v112
	s_nop 1
	v_addc_co_u32_e32 v117, vcc, 0, v113, vcc
	global_load_dwordx4 v[80:83], v[114:115], off offset:2048
	global_load_dwordx4 v[84:87], v[116:117], off
	global_load_dwordx4 v[88:91], v[116:117], off offset:-4096
	s_add_u32 s10, s10, 0x2800
	s_addc_u32 s11, s11, 0
	v_lshl_add_u64 v[112:113], v[36:37], 0, s[10:11]
	v_add_co_u32_e32 v114, vcc, s26, v112
	s_nop 1
	v_addc_co_u32_e32 v115, vcc, 0, v113, vcc
	v_add_co_u32_e32 v116, vcc, s27, v112
	s_nop 1
	v_addc_co_u32_e32 v117, vcc, 0, v113, vcc
	global_load_dwordx4 v[96:99], v[114:115], off offset:2048
	global_load_dwordx4 v[100:103], v[116:117], off
	global_load_dwordx4 v[104:107], v[116:117], off offset:-4096
	s_add_u32 s10, s10, 0x2800
	s_addc_u32 s11, s11, 0
	s_waitcnt vmcnt(6)
	v_pk_mul_f32 v[64:65], v[8:9], v[38:39]
	v_pk_mul_f32 v[66:67], v[10:11], v[40:41]
	v_pk_mul_f32 v[68:69], v[16:17], v[42:43]
	v_pk_mul_f32 v[70:71], v[18:19], v[44:45]
	v_pk_fma_f32 v[64:65], v[4:5], v[26:27], v[64:65]
	v_pk_fma_f32 v[66:67], v[6:7], v[28:29], v[66:67]
	v_pk_fma_f32 v[68:69], v[0:1], v[30:31], v[68:69]
	v_pk_fma_f32 v[70:71], v[2:3], v[32:33], v[70:71]
	v_mov_b32_e32 v26, v38
	v_mov_b32_e32 v27, v39
	v_mov_b32_e32 v28, v40
	v_mov_b32_e32 v29, v41
	v_mov_b32_e32 v30, v42
	v_mov_b32_e32 v31, v43
	v_mov_b32_e32 v32, v44
	v_mov_b32_e32 v33, v45
	v_and_or_b32 v24, v49, s28, v47
	v_and_b32_e32 v51, 32, v50
	v_bitop3_b32 v24, v24, v48, v51 bitop3:0xde
	v_add_u32_e32 v50, 4, v50
	v_add_u32_e32 v49, 64, v49
	v_lshl_add_u64 v[72:73], v[34:35], 0, v[24:25]
	s_waitcnt vmcnt(3)
	v_mov_b32_e32 v52, v80
	v_mov_b32_e32 v53, v81
	v_mov_b32_e32 v54, v82
	v_mov_b32_e32 v55, v83
	v_mov_b32_e32 v56, v84
	v_mov_b32_e32 v57, v85
	v_mov_b32_e32 v58, v86
	v_mov_b32_e32 v59, v87
	v_mov_b32_e32 v60, v88
	v_mov_b32_e32 v61, v89
	v_mov_b32_e32 v62, v90
	v_mov_b32_e32 v63, v91
	v_lshl_add_u64 v[112:113], v[36:37], 0, s[10:11]
	v_add_co_u32_e32 v114, vcc, s26, v112
	s_nop 1
	v_addc_co_u32_e32 v115, vcc, 0, v113, vcc
	v_add_co_u32_e32 v116, vcc, s27, v112
	s_nop 1
	v_addc_co_u32_e32 v117, vcc, 0, v113, vcc
	global_load_dwordx4 v[80:83], v[114:115], off offset:2048
	global_load_dwordx4 v[84:87], v[116:117], off
	global_load_dwordx4 v[88:91], v[116:117], off offset:-4096
	s_add_u32 s10, s10, 0x2800
	s_addc_u32 s11, s11, 0
	v_lshlrev_b32_e32 v38, 16, v52
	v_lshlrev_b32_e32 v40, 16, v56
	v_and_b32_e32 v39, 0xffff0000, v52
	v_and_b32_e32 v41, 0xffff0000, v56
	v_lshlrev_b32_e32 v42, 16, v53
	v_lshlrev_b32_e32 v44, 16, v57
	v_and_b32_e32 v43, 0xffff0000, v53
	v_and_b32_e32 v45, 0xffff0000, v57
	v_lshlrev_b32_e32 v52, 16, v54
	v_lshlrev_b32_e32 v56, 16, v58
	v_and_b32_e32 v53, 0xffff0000, v54
	v_and_b32_e32 v57, 0xffff0000, v58
	v_lshlrev_b32_e32 v54, 16, v55
	v_lshlrev_b32_e32 v58, 16, v59
	v_and_b32_e32 v59, 0xffff0000, v59
	v_and_b32_e32 v55, 0xffff0000, v55
	v_pk_mul_f32 v[38:39], v[38:39], v[40:41]
	v_pk_mul_f32 v[40:41], v[42:43], v[44:45]
	v_pk_mul_f32 v[42:43], v[52:53], v[56:57]
	v_pk_mul_f32 v[44:45], v[54:55], v[58:59]
	v_lshlrev_b32_e32 v74, 16, v60
	v_and_b32_e32 v75, 0xffff0000, v60
	v_lshlrev_b32_e32 v60, 16, v61
	v_and_b32_e32 v61, 0xffff0000, v61
	v_lshlrev_b32_e32 v76, 16, v62
	v_and_b32_e32 v77, 0xffff0000, v62
	v_lshlrev_b32_e32 v62, 16, v63
	v_and_b32_e32 v63, 0xffff0000, v63
	v_pk_fma_f32 v[52:53], v[12:13], v[38:39], v[64:65]
	v_pk_fma_f32 v[54:55], v[14:15], v[40:41], v[66:67]
	v_pk_fma_f32 v[56:57], v[20:21], v[42:43], v[68:69]
	v_pk_fma_f32 v[58:59], v[22:23], v[44:45], v[70:71]
	v_pk_mul_f32 v[52:53], v[52:53], v[74:75]
	v_pk_mul_f32 v[54:55], v[54:55], v[60:61]
	v_pk_mul_f32 v[56:57], v[56:57], v[76:77]
	v_pk_mul_f32 v[58:59], v[58:59], v[62:63]
	v_cvt_pk_bf16_f32 v52, v52, v53
	v_cvt_pk_bf16_f32 v53, v54, v55
	v_cvt_pk_bf16_f32 v54, v56, v57
	v_cvt_pk_bf16_f32 v55, v58, v59
	global_store_dwordx4 v[72:73], v[52:55], off
	v_pk_mul_f32 v[64:65], v[8:9], v[38:39]
	v_pk_mul_f32 v[66:67], v[10:11], v[40:41]
	v_pk_mul_f32 v[68:69], v[16:17], v[42:43]
	v_pk_mul_f32 v[70:71], v[18:19], v[44:45]
	v_pk_fma_f32 v[64:65], v[4:5], v[26:27], v[64:65]
	v_pk_fma_f32 v[66:67], v[6:7], v[28:29], v[66:67]
	v_pk_fma_f32 v[68:69], v[0:1], v[30:31], v[68:69]
	v_pk_fma_f32 v[70:71], v[2:3], v[32:33], v[70:71]
	v_mov_b32_e32 v26, v38
	v_mov_b32_e32 v27, v39
	v_mov_b32_e32 v28, v40
	v_mov_b32_e32 v29, v41
	v_mov_b32_e32 v30, v42
	v_mov_b32_e32 v31, v43
	v_mov_b32_e32 v32, v44
	v_mov_b32_e32 v33, v45
	v_and_or_b32 v24, v49, s28, v47
	v_and_b32_e32 v51, 32, v50
	v_bitop3_b32 v24, v24, v48, v51 bitop3:0xde
	v_add_u32_e32 v50, 4, v50
	v_add_u32_e32 v49, 64, v49
	v_lshl_add_u64 v[72:73], v[34:35], 0, v[24:25]
	s_waitcnt vmcnt(4)
; __device__ __forceinline__ float bf_lo(u32 v) { return __uint_as_float(v << 16); }
; __device__ __forceinline__ float bf_hi(u32 v) { return __uint_as_float(v & 0xFFFF0000u); }
; __device__ __forceinline__ void mixer_phase(const Params& p, char* shm) {
;     ...
;       for (int r = 0; r < 16; ++r) {
;         const u16* zr = z + (size_t)(row0 + r) * DIN;
;         uint4 gb = *(const uint4*)(zr + 2048 + c0);
;         uint4 gc = *(const uint4*)(zr + 3072 + c0);
;         uint4 xt = *(const uint4*)(zr + 4096 + c0);
;         float hh[8], gbf[8], y[8];
;         hh[0] = bf_lo(gc.x) * bf_lo(xt.x); hh[1] = bf_hi(gc.x) * bf_hi(xt.x);
;         hh[2] = bf_lo(gc.y) * bf_lo(xt.y); hh[3] = bf_hi(gc.y) * bf_hi(xt.y);
;         hh[4] = bf_lo(gc.z) * bf_lo(xt.z); hh[5] = bf_hi(gc.z) * bf_hi(xt.z);
;         hh[6] = bf_lo(gc.w) * bf_lo(xt.w); hh[7] = bf_hi(gc.w) * bf_hi(xt.w);
;         gbf[0] = bf_lo(gb.x); gbf[1] = bf_hi(gb.x); gbf[2] = bf_lo(gb.y); gbf[3] = bf_hi(gb.y);
;         gbf[4] = bf_lo(gb.z); gbf[5] = bf_hi(gb.z); gbf[6] = bf_lo(gb.w); gbf[7] = bf_hi(gb.w);
; #pragma unroll
;         for (int e = 0; e < 8; ++e) {
;           y[e] = gbf[e] * (w0[e] * h2[e] + w1[e] * h1[e] + w2[e] * hh[e]);
;           h2[e] = h1[e]; h1[e] = hh[e];
;         }
;         uint4 o;
;         o.x = pack2(y[0], y[1]); o.y = pack2(y[2], y[3]); o.z = pack2(y[4], y[5]); o.w = pack2(y[6], y[7]);
;         *(uint4*)((char*)ymix + tl_off(row0 + r, DA + c0, DM >> 6)) = o;
;       }
	v_mov_b32_e32 v52, v96
	v_mov_b32_e32 v53, v97
	v_mov_b32_e32 v54, v98
	v_mov_b32_e32 v55, v99
	v_mov_b32_e32 v56, v100
	v_mov_b32_e32 v57, v101
	v_mov_b32_e32 v58, v102
	v_mov_b32_e32 v59, v103
	v_mov_b32_e32 v60, v104
	v_mov_b32_e32 v61, v105
	v_mov_b32_e32 v62, v106
	v_mov_b32_e32 v63, v107
	v_lshl_add_u64 v[112:113], v[36:37], 0, s[10:11]
	v_add_co_u32_e32 v114, vcc, s26, v112
	s_nop 1
	v_addc_co_u32_e32 v115, vcc, 0, v113, vcc
	v_add_co_u32_e32 v116, vcc, s27, v112
	s_nop 1
	v_addc_co_u32_e32 v117, vcc, 0, v113, vcc
	global_load_dwordx4 v[96:99], v[114:115], off offset:2048
	global_load_dwordx4 v[100:103], v[116:117], off
	global_load_dwordx4 v[104:107], v[116:117], off offset:-4096
	s_add_u32 s10, s10, 0x2800
	s_addc_u32 s11, s11, 0
	v_lshlrev_b32_e32 v38, 16, v52
	v_lshlrev_b32_e32 v40, 16, v56
	v_and_b32_e32 v39, 0xffff0000, v52
	v_and_b32_e32 v41, 0xffff0000, v56
	v_lshlrev_b32_e32 v42, 16, v53
	v_lshlrev_b32_e32 v44, 16, v57
	v_and_b32_e32 v43, 0xffff0000, v53
	v_and_b32_e32 v45, 0xffff0000, v57
	v_lshlrev_b32_e32 v52, 16, v54
	v_lshlrev_b32_e32 v56, 16, v58
	v_and_b32_e32 v53, 0xffff0000, v54
	v_and_b32_e32 v57, 0xffff0000, v58
	v_lshlrev_b32_e32 v54, 16, v55
	v_lshlrev_b32_e32 v58, 16, v59
	v_and_b32_e32 v59, 0xffff0000, v59
	v_and_b32_e32 v55, 0xffff0000, v55
	v_pk_mul_f32 v[38:39], v[38:39], v[40:41]
	v_pk_mul_f32 v[40:41], v[42:43], v[44:45]
	v_pk_mul_f32 v[42:43], v[52:53], v[56:57]
	v_pk_mul_f32 v[44:45], v[54:55], v[58:59]
	v_lshlrev_b32_e32 v74, 16, v60
	v_and_b32_e32 v75, 0xffff0000, v60
	v_lshlrev_b32_e32 v60, 16, v61
	v_and_b32_e32 v61, 0xffff0000, v61
	v_lshlrev_b32_e32 v76, 16, v62
	v_and_b32_e32 v77, 0xffff0000, v62
	v_lshlrev_b32_e32 v62, 16, v63
	v_and_b32_e32 v63, 0xffff0000, v63
	v_pk_fma_f32 v[52:53], v[12:13], v[38:39], v[64:65]
	v_pk_fma_f32 v[54:55], v[14:15], v[40:41], v[66:67]
	v_pk_fma_f32 v[56:57], v[20:21], v[42:43], v[68:69]
	v_pk_fma_f32 v[58:59], v[22:23], v[44:45], v[70:71]
	v_pk_mul_f32 v[52:53], v[52:53], v[74:75]
	v_pk_mul_f32 v[54:55], v[54:55], v[60:61]
	v_pk_mul_f32 v[56:57], v[56:57], v[76:77]
	v_pk_mul_f32 v[58:59], v[58:59], v[62:63]
	v_cvt_pk_bf16_f32 v52, v52, v53
	v_cvt_pk_bf16_f32 v53, v54, v55
	v_cvt_pk_bf16_f32 v54, v56, v57
	v_cvt_pk_bf16_f32 v55, v58, v59
	global_store_dwordx4 v[72:73], v[52:55], off
	v_pk_mul_f32 v[64:65], v[8:9], v[38:39]
	v_pk_mul_f32 v[66:67], v[10:11], v[40:41]
	v_pk_mul_f32 v[68:69], v[16:17], v[42:43]
	v_pk_mul_f32 v[70:71], v[18:19], v[44:45]
	v_pk_fma_f32 v[64:65], v[4:5], v[26:27], v[64:65]
	v_pk_fma_f32 v[66:67], v[6:7], v[28:29], v[66:67]
	v_pk_fma_f32 v[68:69], v[0:1], v[30:31], v[68:69]
	v_pk_fma_f32 v[70:71], v[2:3], v[32:33], v[70:71]
	v_mov_b32_e32 v26, v38
	v_mov_b32_e32 v27, v39
	v_mov_b32_e32 v28, v40
	v_mov_b32_e32 v29, v41
	v_mov_b32_e32 v30, v42
	v_mov_b32_e32 v31, v43
	v_mov_b32_e32 v32, v44
	v_mov_b32_e32 v33, v45
	v_and_or_b32 v24, v49, s28, v47
	v_and_b32_e32 v51, 32, v50
	v_bitop3_b32 v24, v24, v48, v51 bitop3:0xde
	v_add_u32_e32 v50, 4, v50
	v_add_u32_e32 v49, 64, v49
	v_lshl_add_u64 v[72:73], v[34:35], 0, v[24:25]
	s_waitcnt vmcnt(5)
	v_mov_b32_e32 v52, v80
	v_mov_b32_e32 v53, v81
	v_mov_b32_e32 v54, v82
	v_mov_b32_e32 v55, v83
	v_mov_b32_e32 v56, v84
	v_mov_b32_e32 v57, v85
	v_mov_b32_e32 v58, v86
	v_mov_b32_e32 v59, v87
	v_mov_b32_e32 v60, v88
	v_mov_b32_e32 v61, v89
	v_mov_b32_e32 v62, v90
	v_mov_b32_e32 v63, v91
	v_lshl_add_u64 v[112:113], v[36:37], 0, s[10:11]
	v_add_co_u32_e32 v114, vcc, s26, v112
	s_nop 1
	v_addc_co_u32_e32 v115, vcc, 0, v113, vcc
	v_add_co_u32_e32 v116, vcc, s27, v112
	s_nop 1
	v_addc_co_u32_e32 v117, vcc, 0, v113, vcc
	global_load_dwordx4 v[80:83], v[114:115], off offset:2048
	global_load_dwordx4 v[84:87], v[116:117], off
	global_load_dwordx4 v[88:91], v[116:117], off offset:-4096
	s_add_u32 s10, s10, 0x2800
	s_addc_u32 s11, s11, 0
	v_lshlrev_b32_e32 v38, 16, v52
	v_lshlrev_b32_e32 v40, 16, v56
	v_and_b32_e32 v39, 0xffff0000, v52
	v_and_b32_e32 v41, 0xffff0000, v56
	v_lshlrev_b32_e32 v42, 16, v53
	v_lshlrev_b32_e32 v44, 16, v57
	v_and_b32_e32 v43, 0xffff0000, v53
	v_and_b32_e32 v45, 0xffff0000, v57
	v_lshlrev_b32_e32 v52, 16, v54
	v_lshlrev_b32_e32 v56, 16, v58
	v_and_b32_e32 v53, 0xffff0000, v54
	v_and_b32_e32 v57, 0xffff0000, v58
	v_lshlrev_b32_e32 v54, 16, v55
	v_lshlrev_b32_e32 v58, 16, v59
	v_and_b32_e32 v59, 0xffff0000, v59
	v_and_b32_e32 v55, 0xffff0000, v55
	v_pk_mul_f32 v[38:39], v[38:39], v[40:41]
	v_pk_mul_f32 v[40:41], v[42:43], v[44:45]
	v_pk_mul_f32 v[42:43], v[52:53], v[56:57]
	v_pk_mul_f32 v[44:45], v[54:55], v[58:59]
	v_lshlrev_b32_e32 v74, 16, v60
	v_and_b32_e32 v75, 0xffff0000, v60
	v_lshlrev_b32_e32 v60, 16, v61
	v_and_b32_e32 v61, 0xffff0000, v61
	v_lshlrev_b32_e32 v76, 16, v62
	v_and_b32_e32 v77, 0xffff0000, v62
	v_lshlrev_b32_e32 v62, 16, v63
	v_and_b32_e32 v63, 0xffff0000, v63
	v_pk_fma_f32 v[52:53], v[12:13], v[38:39], v[64:65]
	v_pk_fma_f32 v[54:55], v[14:15], v[40:41], v[66:67]
	v_pk_fma_f32 v[56:57], v[20:21], v[42:43], v[68:69]
	v_pk_fma_f32 v[58:59], v[22:23], v[44:45], v[70:71]
	v_pk_mul_f32 v[52:53], v[52:53], v[74:75]
	v_pk_mul_f32 v[54:55], v[54:55], v[60:61]
	v_pk_mul_f32 v[56:57], v[56:57], v[76:77]
	v_pk_mul_f32 v[58:59], v[58:59], v[62:63]
	v_cvt_pk_bf16_f32 v52, v52, v53
	v_cvt_pk_bf16_f32 v53, v54, v55
	v_cvt_pk_bf16_f32 v54, v56, v57
	v_cvt_pk_bf16_f32 v55, v58, v59
	global_store_dwordx4 v[72:73], v[52:55], off
	v_pk_mul_f32 v[64:65], v[8:9], v[38:39]
	v_pk_mul_f32 v[66:67], v[10:11], v[40:41]
	v_pk_mul_f32 v[68:69], v[16:17], v[42:43]
	v_pk_mul_f32 v[70:71], v[18:19], v[44:45]
	v_pk_fma_f32 v[64:65], v[4:5], v[26:27], v[64:65]
	v_pk_fma_f32 v[66:67], v[6:7], v[28:29], v[66:67]
	v_pk_fma_f32 v[68:69], v[0:1], v[30:31], v[68:69]
	v_pk_fma_f32 v[70:71], v[2:3], v[32:33], v[70:71]
	v_mov_b32_e32 v26, v38
	v_mov_b32_e32 v27, v39
	v_mov_b32_e32 v28, v40
	v_mov_b32_e32 v29, v41
	v_mov_b32_e32 v30, v42
	v_mov_b32_e32 v31, v43
	v_mov_b32_e32 v32, v44
	v_mov_b32_e32 v33, v45
	v_and_or_b32 v24, v49, s28, v47
	v_and_b32_e32 v51, 32, v50
	v_bitop3_b32 v24, v24, v48, v51 bitop3:0xde
	v_add_u32_e32 v50, 4, v50
	v_add_u32_e32 v49, 64, v49
	v_lshl_add_u64 v[72:73], v[34:35], 0, v[24:25]
	s_waitcnt vmcnt(5)
; __device__ __forceinline__ float bf_lo(u32 v) { return __uint_as_float(v << 16); }
; __device__ __forceinline__ float bf_hi(u32 v) { return __uint_as_float(v & 0xFFFF0000u); }
; __device__ __forceinline__ void mixer_phase(const Params& p, char* shm) {
;     ...
;       for (int r = 0; r < 16; ++r) {
;         const u16* zr = z + (size_t)(row0 + r) * DIN;
;         uint4 gb = *(const uint4*)(zr + 2048 + c0);
;         uint4 gc = *(const uint4*)(zr + 3072 + c0);
;         uint4 xt = *(const uint4*)(zr + 4096 + c0);
;         float hh[8], gbf[8], y[8];
;         hh[0] = bf_lo(gc.x) * bf_lo(xt.x); hh[1] = bf_hi(gc.x) * bf_hi(xt.x);
;         hh[2] = bf_lo(gc.y) * bf_lo(xt.y); hh[3] = bf_hi(gc.y) * bf_hi(xt.y);
;         hh[4] = bf_lo(gc.z) * bf_lo(xt.z); hh[5] = bf_hi(gc.z) * bf_hi(xt.z);
;         hh[6] = bf_lo(gc.w) * bf_lo(xt.w); hh[7] = bf_hi(gc.w) * bf_hi(xt.w);
;         gbf[0] = bf_lo(gb.x); gbf[1] = bf_hi(gb.x); gbf[2] = bf_lo(gb.y); gbf[3] = bf_hi(gb.y);
;         gbf[4] = bf_lo(gb.z); gbf[5] = bf_hi(gb.z); gbf[6] = bf_lo(gb.w); gbf[7] = bf_hi(gb.w);
; #pragma unroll
;         for (int e = 0; e < 8; ++e) {
;           y[e] = gbf[e] * (w0[e] * h2[e] + w1[e] * h1[e] + w2[e] * hh[e]);
;           h2[e] = h1[e]; h1[e] = hh[e];
;         }
;         uint4 o;
;         o.x = pack2(y[0], y[1]); o.y = pack2(y[2], y[3]); o.z = pack2(y[4], y[5]); o.w = pack2(y[6], y[7]);
;         *(uint4*)((char*)ymix + tl_off(row0 + r, DA + c0, DM >> 6)) = o;
;       }
	v_mov_b32_e32 v52, v96
	v_mov_b32_e32 v53, v97
	v_mov_b32_e32 v54, v98
	v_mov_b32_e32 v55, v99
	v_mov_b32_e32 v56, v100
	v_mov_b32_e32 v57, v101
	v_mov_b32_e32 v58, v102
	v_mov_b32_e32 v59, v103
	v_mov_b32_e32 v60, v104
	v_mov_b32_e32 v61, v105
	v_mov_b32_e32 v62, v106
	v_mov_b32_e32 v63, v107
	v_lshl_add_u64 v[112:113], v[36:37], 0, s[10:11]
	v_add_co_u32_e32 v114, vcc, s26, v112
	s_nop 1
	v_addc_co_u32_e32 v115, vcc, 0, v113, vcc
	v_add_co_u32_e32 v116, vcc, s27, v112
	s_nop 1
	v_addc_co_u32_e32 v117, vcc, 0, v113, vcc
	global_load_dwordx4 v[96:99], v[114:115], off offset:2048
	global_load_dwordx4 v[100:103], v[116:117], off
	global_load_dwordx4 v[104:107], v[116:117], off offset:-4096
	s_add_u32 s10, s10, 0x2800
	s_addc_u32 s11, s11, 0
	v_lshlrev_b32_e32 v38, 16, v52
	v_lshlrev_b32_e32 v40, 16, v56
	v_and_b32_e32 v39, 0xffff0000, v52
	v_and_b32_e32 v41, 0xffff0000, v56
	v_lshlrev_b32_e32 v42, 16, v53
	v_lshlrev_b32_e32 v44, 16, v57
	v_and_b32_e32 v43, 0xffff0000, v53
	v_and_b32_e32 v45, 0xffff0000, v57
	v_lshlrev_b32_e32 v52, 16, v54
	v_lshlrev_b32_e32 v56, 16, v58
	v_and_b32_e32 v53, 0xffff0000, v54
	v_and_b32_e32 v57, 0xffff0000, v58
	v_lshlrev_b32_e32 v54, 16, v55
	v_lshlrev_b32_e32 v58, 16, v59
	v_and_b32_e32 v59, 0xffff0000, v59
	v_and_b32_e32 v55, 0xffff0000, v55
	v_pk_mul_f32 v[38:39], v[38:39], v[40:41]
	v_pk_mul_f32 v[40:41], v[42:43], v[44:45]
	v_pk_mul_f32 v[42:43], v[52:53], v[56:57]
	v_pk_mul_f32 v[44:45], v[54:55], v[58:59]
	v_lshlrev_b32_e32 v74, 16, v60
	v_and_b32_e32 v75, 0xffff0000, v60
	v_lshlrev_b32_e32 v60, 16, v61
	v_and_b32_e32 v61, 0xffff0000, v61
	v_lshlrev_b32_e32 v76, 16, v62
	v_and_b32_e32 v77, 0xffff0000, v62
	v_lshlrev_b32_e32 v62, 16, v63
	v_and_b32_e32 v63, 0xffff0000, v63
	v_pk_fma_f32 v[52:53], v[12:13], v[38:39], v[64:65]
	v_pk_fma_f32 v[54:55], v[14:15], v[40:41], v[66:67]
	v_pk_fma_f32 v[56:57], v[20:21], v[42:43], v[68:69]
	v_pk_fma_f32 v[58:59], v[22:23], v[44:45], v[70:71]
	v_pk_mul_f32 v[52:53], v[52:53], v[74:75]
	v_pk_mul_f32 v[54:55], v[54:55], v[60:61]
	v_pk_mul_f32 v[56:57], v[56:57], v[76:77]
	v_pk_mul_f32 v[58:59], v[58:59], v[62:63]
	v_cvt_pk_bf16_f32 v52, v52, v53
	v_cvt_pk_bf16_f32 v53, v54, v55
	v_cvt_pk_bf16_f32 v54, v56, v57
	v_cvt_pk_bf16_f32 v55, v58, v59
	global_store_dwordx4 v[72:73], v[52:55], off
	v_pk_mul_f32 v[64:65], v[8:9], v[38:39]
	v_pk_mul_f32 v[66:67], v[10:11], v[40:41]
	v_pk_mul_f32 v[68:69], v[16:17], v[42:43]
	v_pk_mul_f32 v[70:71], v[18:19], v[44:45]
	v_pk_fma_f32 v[64:65], v[4:5], v[26:27], v[64:65]
	v_pk_fma_f32 v[66:67], v[6:7], v[28:29], v[66:67]
	v_pk_fma_f32 v[68:69], v[0:1], v[30:31], v[68:69]
	v_pk_fma_f32 v[70:71], v[2:3], v[32:33], v[70:71]
	v_mov_b32_e32 v26, v38
	v_mov_b32_e32 v27, v39
	v_mov_b32_e32 v28, v40
	v_mov_b32_e32 v29, v41
	v_mov_b32_e32 v30, v42
	v_mov_b32_e32 v31, v43
	v_mov_b32_e32 v32, v44
	v_mov_b32_e32 v33, v45
	v_and_or_b32 v24, v49, s28, v47
	v_and_b32_e32 v51, 32, v50
	v_bitop3_b32 v24, v24, v48, v51 bitop3:0xde
	v_add_u32_e32 v50, 4, v50
	v_add_u32_e32 v49, 64, v49
	v_lshl_add_u64 v[72:73], v[34:35], 0, v[24:25]
	s_waitcnt vmcnt(5)
	v_mov_b32_e32 v52, v80
	v_mov_b32_e32 v53, v81
	v_mov_b32_e32 v54, v82
	v_mov_b32_e32 v55, v83
	v_mov_b32_e32 v56, v84
	v_mov_b32_e32 v57, v85
	v_mov_b32_e32 v58, v86
	v_mov_b32_e32 v59, v87
	v_mov_b32_e32 v60, v88
	v_mov_b32_e32 v61, v89
	v_mov_b32_e32 v62, v90
	v_mov_b32_e32 v63, v91
	v_lshl_add_u64 v[112:113], v[36:37], 0, s[10:11]
	v_add_co_u32_e32 v114, vcc, s26, v112
	s_nop 1
	v_addc_co_u32_e32 v115, vcc, 0, v113, vcc
	v_add_co_u32_e32 v116, vcc, s27, v112
	s_nop 1
	v_addc_co_u32_e32 v117, vcc, 0, v113, vcc
	global_load_dwordx4 v[80:83], v[114:115], off offset:2048
	global_load_dwordx4 v[84:87], v[116:117], off
	global_load_dwordx4 v[88:91], v[116:117], off offset:-4096
	s_add_u32 s10, s10, 0x2800
	s_addc_u32 s11, s11, 0
	v_lshlrev_b32_e32 v38, 16, v52
	v_lshlrev_b32_e32 v40, 16, v56
	v_and_b32_e32 v39, 0xffff0000, v52
	v_and_b32_e32 v41, 0xffff0000, v56
	v_lshlrev_b32_e32 v42, 16, v53
	v_lshlrev_b32_e32 v44, 16, v57
	v_and_b32_e32 v43, 0xffff0000, v53
	v_and_b32_e32 v45, 0xffff0000, v57
	v_lshlrev_b32_e32 v52, 16, v54
	v_lshlrev_b32_e32 v56, 16, v58
	v_and_b32_e32 v53, 0xffff0000, v54
	v_and_b32_e32 v57, 0xffff0000, v58
	v_lshlrev_b32_e32 v54, 16, v55
	v_lshlrev_b32_e32 v58, 16, v59
	v_and_b32_e32 v59, 0xffff0000, v59
	v_and_b32_e32 v55, 0xffff0000, v55
	v_pk_mul_f32 v[38:39], v[38:39], v[40:41]
	v_pk_mul_f32 v[40:41], v[42:43], v[44:45]
	v_pk_mul_f32 v[42:43], v[52:53], v[56:57]
	v_pk_mul_f32 v[44:45], v[54:55], v[58:59]
	v_lshlrev_b32_e32 v74, 16, v60
	v_and_b32_e32 v75, 0xffff0000, v60
	v_lshlrev_b32_e32 v60, 16, v61
	v_and_b32_e32 v61, 0xffff0000, v61
	v_lshlrev_b32_e32 v76, 16, v62
	v_and_b32_e32 v77, 0xffff0000, v62
	v_lshlrev_b32_e32 v62, 16, v63
	v_and_b32_e32 v63, 0xffff0000, v63
	v_pk_fma_f32 v[52:53], v[12:13], v[38:39], v[64:65]
	v_pk_fma_f32 v[54:55], v[14:15], v[40:41], v[66:67]
	v_pk_fma_f32 v[56:57], v[20:21], v[42:43], v[68:69]
	v_pk_fma_f32 v[58:59], v[22:23], v[44:45], v[70:71]
	v_pk_mul_f32 v[52:53], v[52:53], v[74:75]
	v_pk_mul_f32 v[54:55], v[54:55], v[60:61]
	v_pk_mul_f32 v[56:57], v[56:57], v[76:77]
	v_pk_mul_f32 v[58:59], v[58:59], v[62:63]
	v_cvt_pk_bf16_f32 v52, v52, v53
	v_cvt_pk_bf16_f32 v53, v54, v55
	v_cvt_pk_bf16_f32 v54, v56, v57
	v_cvt_pk_bf16_f32 v55, v58, v59
	global_store_dwordx4 v[72:73], v[52:55], off
	v_pk_mul_f32 v[64:65], v[8:9], v[38:39]
	v_pk_mul_f32 v[66:67], v[10:11], v[40:41]
	v_pk_mul_f32 v[68:69], v[16:17], v[42:43]
	v_pk_mul_f32 v[70:71], v[18:19], v[44:45]
	v_pk_fma_f32 v[64:65], v[4:5], v[26:27], v[64:65]
	v_pk_fma_f32 v[66:67], v[6:7], v[28:29], v[66:67]
	v_pk_fma_f32 v[68:69], v[0:1], v[30:31], v[68:69]
	v_pk_fma_f32 v[70:71], v[2:3], v[32:33], v[70:71]
	v_mov_b32_e32 v26, v38
	v_mov_b32_e32 v27, v39
	v_mov_b32_e32 v28, v40
	v_mov_b32_e32 v29, v41
	v_mov_b32_e32 v30, v42
	v_mov_b32_e32 v31, v43
	v_mov_b32_e32 v32, v44
	v_mov_b32_e32 v33, v45
	v_and_or_b32 v24, v49, s28, v47
	v_and_b32_e32 v51, 32, v50
	v_bitop3_b32 v24, v24, v48, v51 bitop3:0xde
	v_add_u32_e32 v50, 4, v50
	v_add_u32_e32 v49, 64, v49
	v_lshl_add_u64 v[72:73], v[34:35], 0, v[24:25]
	s_waitcnt vmcnt(5)
; __device__ __forceinline__ float bf_lo(u32 v) { return __uint_as_float(v << 16); }
; __device__ __forceinline__ float bf_hi(u32 v) { return __uint_as_float(v & 0xFFFF0000u); }
; __device__ __forceinline__ void mixer_phase(const Params& p, char* shm) {
;     ...
;       for (int r = 0; r < 16; ++r) {
;         const u16* zr = z + (size_t)(row0 + r) * DIN;
;         uint4 gb = *(const uint4*)(zr + 2048 + c0);
;         uint4 gc = *(const uint4*)(zr + 3072 + c0);
;         uint4 xt = *(const uint4*)(zr + 4096 + c0);
;         float hh[8], gbf[8], y[8];
;         hh[0] = bf_lo(gc.x) * bf_lo(xt.x); hh[1] = bf_hi(gc.x) * bf_hi(xt.x);
;         hh[2] = bf_lo(gc.y) * bf_lo(xt.y); hh[3] = bf_hi(gc.y) * bf_hi(xt.y);
;         hh[4] = bf_lo(gc.z) * bf_lo(xt.z); hh[5] = bf_hi(gc.z) * bf_hi(xt.z);
;         hh[6] = bf_lo(gc.w) * bf_lo(xt.w); hh[7] = bf_hi(gc.w) * bf_hi(xt.w);
;         gbf[0] = bf_lo(gb.x); gbf[1] = bf_hi(gb.x); gbf[2] = bf_lo(gb.y); gbf[3] = bf_hi(gb.y);
;         gbf[4] = bf_lo(gb.z); gbf[5] = bf_hi(gb.z); gbf[6] = bf_lo(gb.w); gbf[7] = bf_hi(gb.w);
; #pragma unroll
;         for (int e = 0; e < 8; ++e) {
;           y[e] = gbf[e] * (w0[e] * h2[e] + w1[e] * h1[e] + w2[e] * hh[e]);
;           h2[e] = h1[e]; h1[e] = hh[e];
;         }
;         uint4 o;
;         o.x = pack2(y[0], y[1]); o.y = pack2(y[2], y[3]); o.z = pack2(y[4], y[5]); o.w = pack2(y[6], y[7]);
;         *(uint4*)((char*)ymix + tl_off(row0 + r, DA + c0, DM >> 6)) = o;
;       }
	v_mov_b32_e32 v52, v96
	v_mov_b32_e32 v53, v97
	v_mov_b32_e32 v54, v98
	v_mov_b32_e32 v55, v99
	v_mov_b32_e32 v56, v100
	v_mov_b32_e32 v57, v101
	v_mov_b32_e32 v58, v102
	v_mov_b32_e32 v59, v103
	v_mov_b32_e32 v60, v104
	v_mov_b32_e32 v61, v105
	v_mov_b32_e32 v62, v106
	v_mov_b32_e32 v63, v107
	v_lshl_add_u64 v[112:113], v[36:37], 0, s[10:11]
	v_add_co_u32_e32 v114, vcc, s26, v112
	s_nop 1
	v_addc_co_u32_e32 v115, vcc, 0, v113, vcc
	v_add_co_u32_e32 v116, vcc, s27, v112
	s_nop 1
	v_addc_co_u32_e32 v117, vcc, 0, v113, vcc
	global_load_dwordx4 v[96:99], v[114:115], off offset:2048
	global_load_dwordx4 v[100:103], v[116:117], off
	global_load_dwordx4 v[104:107], v[116:117], off offset:-4096
	s_add_u32 s10, s10, 0x2800
	s_addc_u32 s11, s11, 0
	v_lshlrev_b32_e32 v38, 16, v52
	v_lshlrev_b32_e32 v40, 16, v56
	v_and_b32_e32 v39, 0xffff0000, v52
	v_and_b32_e32 v41, 0xffff0000, v56
	v_lshlrev_b32_e32 v42, 16, v53
	v_lshlrev_b32_e32 v44, 16, v57
	v_and_b32_e32 v43, 0xffff0000, v53
	v_and_b32_e32 v45, 0xffff0000, v57
	v_lshlrev_b32_e32 v52, 16, v54
	v_lshlrev_b32_e32 v56, 16, v58
	v_and_b32_e32 v53, 0xffff0000, v54
	v_and_b32_e32 v57, 0xffff0000, v58
	v_lshlrev_b32_e32 v54, 16, v55
	v_lshlrev_b32_e32 v58, 16, v59
	v_and_b32_e32 v59, 0xffff0000, v59
	v_and_b32_e32 v55, 0xffff0000, v55
	v_pk_mul_f32 v[38:39], v[38:39], v[40:41]
	v_pk_mul_f32 v[40:41], v[42:43], v[44:45]
	v_pk_mul_f32 v[42:43], v[52:53], v[56:57]
	v_pk_mul_f32 v[44:45], v[54:55], v[58:59]
	v_lshlrev_b32_e32 v74, 16, v60
	v_and_b32_e32 v75, 0xffff0000, v60
	v_lshlrev_b32_e32 v60, 16, v61
	v_and_b32_e32 v61, 0xffff0000, v61
	v_lshlrev_b32_e32 v76, 16, v62
	v_and_b32_e32 v77, 0xffff0000, v62
	v_lshlrev_b32_e32 v62, 16, v63
	v_and_b32_e32 v63, 0xffff0000, v63
	v_pk_fma_f32 v[52:53], v[12:13], v[38:39], v[64:65]
	v_pk_fma_f32 v[54:55], v[14:15], v[40:41], v[66:67]
	v_pk_fma_f32 v[56:57], v[20:21], v[42:43], v[68:69]
	v_pk_fma_f32 v[58:59], v[22:23], v[44:45], v[70:71]
	v_pk_mul_f32 v[52:53], v[52:53], v[74:75]
	v_pk_mul_f32 v[54:55], v[54:55], v[60:61]
	v_pk_mul_f32 v[56:57], v[56:57], v[76:77]
	v_pk_mul_f32 v[58:59], v[58:59], v[62:63]
	v_cvt_pk_bf16_f32 v52, v52, v53
	v_cvt_pk_bf16_f32 v53, v54, v55
	v_cvt_pk_bf16_f32 v54, v56, v57
	v_cvt_pk_bf16_f32 v55, v58, v59
	global_store_dwordx4 v[72:73], v[52:55], off
	v_pk_mul_f32 v[64:65], v[8:9], v[38:39]
	v_pk_mul_f32 v[66:67], v[10:11], v[40:41]
	v_pk_mul_f32 v[68:69], v[16:17], v[42:43]
	v_pk_mul_f32 v[70:71], v[18:19], v[44:45]
	v_pk_fma_f32 v[64:65], v[4:5], v[26:27], v[64:65]
	v_pk_fma_f32 v[66:67], v[6:7], v[28:29], v[66:67]
	v_pk_fma_f32 v[68:69], v[0:1], v[30:31], v[68:69]
	v_pk_fma_f32 v[70:71], v[2:3], v[32:33], v[70:71]
	v_mov_b32_e32 v26, v38
	v_mov_b32_e32 v27, v39
	v_mov_b32_e32 v28, v40
	v_mov_b32_e32 v29, v41
	v_mov_b32_e32 v30, v42
	v_mov_b32_e32 v31, v43
	v_mov_b32_e32 v32, v44
	v_mov_b32_e32 v33, v45
	v_and_or_b32 v24, v49, s28, v47
	v_and_b32_e32 v51, 32, v50
	v_bitop3_b32 v24, v24, v48, v51 bitop3:0xde
	v_add_u32_e32 v50, 4, v50
	v_add_u32_e32 v49, 64, v49
	v_lshl_add_u64 v[72:73], v[34:35], 0, v[24:25]
	s_waitcnt vmcnt(5)
	v_mov_b32_e32 v52, v80
	v_mov_b32_e32 v53, v81
	v_mov_b32_e32 v54, v82
	v_mov_b32_e32 v55, v83
	v_mov_b32_e32 v56, v84
	v_mov_b32_e32 v57, v85
	v_mov_b32_e32 v58, v86
	v_mov_b32_e32 v59, v87
	v_mov_b32_e32 v60, v88
	v_mov_b32_e32 v61, v89
	v_mov_b32_e32 v62, v90
	v_mov_b32_e32 v63, v91
	v_lshl_add_u64 v[112:113], v[36:37], 0, s[10:11]
	v_add_co_u32_e32 v114, vcc, s26, v112
	s_nop 1
	v_addc_co_u32_e32 v115, vcc, 0, v113, vcc
	v_add_co_u32_e32 v116, vcc, s27, v112
	s_nop 1
	v_addc_co_u32_e32 v117, vcc, 0, v113, vcc
	global_load_dwordx4 v[80:83], v[114:115], off offset:2048
	global_load_dwordx4 v[84:87], v[116:117], off
	global_load_dwordx4 v[88:91], v[116:117], off offset:-4096
	s_add_u32 s10, s10, 0x2800
	s_addc_u32 s11, s11, 0
	v_lshlrev_b32_e32 v38, 16, v52
	v_lshlrev_b32_e32 v40, 16, v56
	v_and_b32_e32 v39, 0xffff0000, v52
	v_and_b32_e32 v41, 0xffff0000, v56
	v_lshlrev_b32_e32 v42, 16, v53
	v_lshlrev_b32_e32 v44, 16, v57
	v_and_b32_e32 v43, 0xffff0000, v53
	v_and_b32_e32 v45, 0xffff0000, v57
	v_lshlrev_b32_e32 v52, 16, v54
	v_lshlrev_b32_e32 v56, 16, v58
	v_and_b32_e32 v53, 0xffff0000, v54
	v_and_b32_e32 v57, 0xffff0000, v58
	v_lshlrev_b32_e32 v54, 16, v55
	v_lshlrev_b32_e32 v58, 16, v59
	v_and_b32_e32 v59, 0xffff0000, v59
	v_and_b32_e32 v55, 0xffff0000, v55
	v_pk_mul_f32 v[38:39], v[38:39], v[40:41]
	v_pk_mul_f32 v[40:41], v[42:43], v[44:45]
	v_pk_mul_f32 v[42:43], v[52:53], v[56:57]
	v_pk_mul_f32 v[44:45], v[54:55], v[58:59]
	v_lshlrev_b32_e32 v74, 16, v60
	v_and_b32_e32 v75, 0xffff0000, v60
	v_lshlrev_b32_e32 v60, 16, v61
	v_and_b32_e32 v61, 0xffff0000, v61
	v_lshlrev_b32_e32 v76, 16, v62
	v_and_b32_e32 v77, 0xffff0000, v62
	v_lshlrev_b32_e32 v62, 16, v63
	v_and_b32_e32 v63, 0xffff0000, v63
	v_pk_fma_f32 v[52:53], v[12:13], v[38:39], v[64:65]
	v_pk_fma_f32 v[54:55], v[14:15], v[40:41], v[66:67]
	v_pk_fma_f32 v[56:57], v[20:21], v[42:43], v[68:69]
	v_pk_fma_f32 v[58:59], v[22:23], v[44:45], v[70:71]
	v_pk_mul_f32 v[52:53], v[52:53], v[74:75]
	v_pk_mul_f32 v[54:55], v[54:55], v[60:61]
	v_pk_mul_f32 v[56:57], v[56:57], v[76:77]
	v_pk_mul_f32 v[58:59], v[58:59], v[62:63]
	v_cvt_pk_bf16_f32 v52, v52, v53
	v_cvt_pk_bf16_f32 v53, v54, v55
	v_cvt_pk_bf16_f32 v54, v56, v57
	v_cvt_pk_bf16_f32 v55, v58, v59
	global_store_dwordx4 v[72:73], v[52:55], off
	v_pk_mul_f32 v[64:65], v[8:9], v[38:39]
	v_pk_mul_f32 v[66:67], v[10:11], v[40:41]
	v_pk_mul_f32 v[68:69], v[16:17], v[42:43]
	v_pk_mul_f32 v[70:71], v[18:19], v[44:45]
	v_pk_fma_f32 v[64:65], v[4:5], v[26:27], v[64:65]
	v_pk_fma_f32 v[66:67], v[6:7], v[28:29], v[66:67]
	v_pk_fma_f32 v[68:69], v[0:1], v[30:31], v[68:69]
	v_pk_fma_f32 v[70:71], v[2:3], v[32:33], v[70:71]
	v_mov_b32_e32 v26, v38
	v_mov_b32_e32 v27, v39
	v_mov_b32_e32 v28, v40
	v_mov_b32_e32 v29, v41
	v_mov_b32_e32 v30, v42
	v_mov_b32_e32 v31, v43
	v_mov_b32_e32 v32, v44
	v_mov_b32_e32 v33, v45
	v_and_or_b32 v24, v49, s28, v47
	v_and_b32_e32 v51, 32, v50
	v_bitop3_b32 v24, v24, v48, v51 bitop3:0xde
	v_add_u32_e32 v50, 4, v50
	v_add_u32_e32 v49, 64, v49
	v_lshl_add_u64 v[72:73], v[34:35], 0, v[24:25]
	s_waitcnt vmcnt(5)
; __device__ __forceinline__ float bf_lo(u32 v) { return __uint_as_float(v << 16); }
; __device__ __forceinline__ float bf_hi(u32 v) { return __uint_as_float(v & 0xFFFF0000u); }
; __device__ __forceinline__ void mixer_phase(const Params& p, char* shm) {
;     ...
;       for (int r = 0; r < 16; ++r) {
;         const u16* zr = z + (size_t)(row0 + r) * DIN;
;         uint4 gb = *(const uint4*)(zr + 2048 + c0);
;         uint4 gc = *(const uint4*)(zr + 3072 + c0);
;         uint4 xt = *(const uint4*)(zr + 4096 + c0);
;         float hh[8], gbf[8], y[8];
;         hh[0] = bf_lo(gc.x) * bf_lo(xt.x); hh[1] = bf_hi(gc.x) * bf_hi(xt.x);
;         hh[2] = bf_lo(gc.y) * bf_lo(xt.y); hh[3] = bf_hi(gc.y) * bf_hi(xt.y);
;         hh[4] = bf_lo(gc.z) * bf_lo(xt.z); hh[5] = bf_hi(gc.z) * bf_hi(xt.z);
;         hh[6] = bf_lo(gc.w) * bf_lo(xt.w); hh[7] = bf_hi(gc.w) * bf_hi(xt.w);
;         gbf[0] = bf_lo(gb.x); gbf[1] = bf_hi(gb.x); gbf[2] = bf_lo(gb.y); gbf[3] = bf_hi(gb.y);
;         gbf[4] = bf_lo(gb.z); gbf[5] = bf_hi(gb.z); gbf[6] = bf_lo(gb.w); gbf[7] = bf_hi(gb.w);
; #pragma unroll
;         for (int e = 0; e < 8; ++e) {
;           y[e] = gbf[e] * (w0[e] * h2[e] + w1[e] * h1[e] + w2[e] * hh[e]);
;           h2[e] = h1[e]; h1[e] = hh[e];
;         }
;         uint4 o;
;         o.x = pack2(y[0], y[1]); o.y = pack2(y[2], y[3]); o.z = pack2(y[4], y[5]); o.w = pack2(y[6], y[7]);
;         *(uint4*)((char*)ymix + tl_off(row0 + r, DA + c0, DM >> 6)) = o;
;       }
	v_mov_b32_e32 v52, v96
	v_mov_b32_e32 v53, v97
	v_mov_b32_e32 v54, v98
	v_mov_b32_e32 v55, v99
	v_mov_b32_e32 v56, v100
	v_mov_b32_e32 v57, v101
	v_mov_b32_e32 v58, v102
	v_mov_b32_e32 v59, v103
	v_mov_b32_e32 v60, v104
	v_mov_b32_e32 v61, v105
	v_mov_b32_e32 v62, v106
	v_mov_b32_e32 v63, v107
	v_lshl_add_u64 v[112:113], v[36:37], 0, s[10:11]
	v_add_co_u32_e32 v114, vcc, s26, v112
	s_nop 1
	v_addc_co_u32_e32 v115, vcc, 0, v113, vcc
	v_add_co_u32_e32 v116, vcc, s27, v112
	s_nop 1
	v_addc_co_u32_e32 v117, vcc, 0, v113, vcc
	global_load_dwordx4 v[96:99], v[114:115], off offset:2048
	global_load_dwordx4 v[100:103], v[116:117], off
	global_load_dwordx4 v[104:107], v[116:117], off offset:-4096
	s_add_u32 s10, s10, 0x2800
	s_addc_u32 s11, s11, 0
	v_lshlrev_b32_e32 v38, 16, v52
	v_lshlrev_b32_e32 v40, 16, v56
	v_and_b32_e32 v39, 0xffff0000, v52
	v_and_b32_e32 v41, 0xffff0000, v56
	v_lshlrev_b32_e32 v42, 16, v53
	v_lshlrev_b32_e32 v44, 16, v57
	v_and_b32_e32 v43, 0xffff0000, v53
	v_and_b32_e32 v45, 0xffff0000, v57
	v_lshlrev_b32_e32 v52, 16, v54
	v_lshlrev_b32_e32 v56, 16, v58
	v_and_b32_e32 v53, 0xffff0000, v54
	v_and_b32_e32 v57, 0xffff0000, v58
	v_lshlrev_b32_e32 v54, 16, v55
	v_lshlrev_b32_e32 v58, 16, v59
	v_and_b32_e32 v59, 0xffff0000, v59
	v_and_b32_e32 v55, 0xffff0000, v55
	v_pk_mul_f32 v[38:39], v[38:39], v[40:41]
	v_pk_mul_f32 v[40:41], v[42:43], v[44:45]
	v_pk_mul_f32 v[42:43], v[52:53], v[56:57]
	v_pk_mul_f32 v[44:45], v[54:55], v[58:59]
	v_lshlrev_b32_e32 v74, 16, v60
	v_and_b32_e32 v75, 0xffff0000, v60
	v_lshlrev_b32_e32 v60, 16, v61
	v_and_b32_e32 v61, 0xffff0000, v61
	v_lshlrev_b32_e32 v76, 16, v62
	v_and_b32_e32 v77, 0xffff0000, v62
	v_lshlrev_b32_e32 v62, 16, v63
	v_and_b32_e32 v63, 0xffff0000, v63
	v_pk_fma_f32 v[52:53], v[12:13], v[38:39], v[64:65]
	v_pk_fma_f32 v[54:55], v[14:15], v[40:41], v[66:67]
	v_pk_fma_f32 v[56:57], v[20:21], v[42:43], v[68:69]
	v_pk_fma_f32 v[58:59], v[22:23], v[44:45], v[70:71]
	v_pk_mul_f32 v[52:53], v[52:53], v[74:75]
	v_pk_mul_f32 v[54:55], v[54:55], v[60:61]
	v_pk_mul_f32 v[56:57], v[56:57], v[76:77]
	v_pk_mul_f32 v[58:59], v[58:59], v[62:63]
	v_cvt_pk_bf16_f32 v52, v52, v53
	v_cvt_pk_bf16_f32 v53, v54, v55
	v_cvt_pk_bf16_f32 v54, v56, v57
	v_cvt_pk_bf16_f32 v55, v58, v59
	global_store_dwordx4 v[72:73], v[52:55], off
	v_pk_mul_f32 v[64:65], v[8:9], v[38:39]
	v_pk_mul_f32 v[66:67], v[10:11], v[40:41]
	v_pk_mul_f32 v[68:69], v[16:17], v[42:43]
	v_pk_mul_f32 v[70:71], v[18:19], v[44:45]
	v_pk_fma_f32 v[64:65], v[4:5], v[26:27], v[64:65]
	v_pk_fma_f32 v[66:67], v[6:7], v[28:29], v[66:67]
	v_pk_fma_f32 v[68:69], v[0:1], v[30:31], v[68:69]
	v_pk_fma_f32 v[70:71], v[2:3], v[32:33], v[70:71]
	v_mov_b32_e32 v26, v38
	v_mov_b32_e32 v27, v39
	v_mov_b32_e32 v28, v40
	v_mov_b32_e32 v29, v41
	v_mov_b32_e32 v30, v42
	v_mov_b32_e32 v31, v43
	v_mov_b32_e32 v32, v44
	v_mov_b32_e32 v33, v45
	v_and_or_b32 v24, v49, s28, v47
	v_and_b32_e32 v51, 32, v50
	v_bitop3_b32 v24, v24, v48, v51 bitop3:0xde
	v_add_u32_e32 v50, 4, v50
	v_add_u32_e32 v49, 64, v49
	v_lshl_add_u64 v[72:73], v[34:35], 0, v[24:25]
	s_waitcnt vmcnt(5)
	v_mov_b32_e32 v52, v80
	v_mov_b32_e32 v53, v81
	v_mov_b32_e32 v54, v82
	v_mov_b32_e32 v55, v83
	v_mov_b32_e32 v56, v84
	v_mov_b32_e32 v57, v85
	v_mov_b32_e32 v58, v86
	v_mov_b32_e32 v59, v87
	v_mov_b32_e32 v60, v88
	v_mov_b32_e32 v61, v89
	v_mov_b32_e32 v62, v90
	v_mov_b32_e32 v63, v91
	v_lshl_add_u64 v[112:113], v[36:37], 0, s[10:11]
	v_add_co_u32_e32 v114, vcc, s26, v112
	s_nop 1
	v_addc_co_u32_e32 v115, vcc, 0, v113, vcc
	v_add_co_u32_e32 v116, vcc, s27, v112
	s_nop 1
	v_addc_co_u32_e32 v117, vcc, 0, v113, vcc
	global_load_dwordx4 v[80:83], v[114:115], off offset:2048
	global_load_dwordx4 v[84:87], v[116:117], off
	global_load_dwordx4 v[88:91], v[116:117], off offset:-4096
	s_add_u32 s10, s10, 0x2800
	s_addc_u32 s11, s11, 0
	v_lshlrev_b32_e32 v38, 16, v52
	v_lshlrev_b32_e32 v40, 16, v56
	v_and_b32_e32 v39, 0xffff0000, v52
	v_and_b32_e32 v41, 0xffff0000, v56
	v_lshlrev_b32_e32 v42, 16, v53
	v_lshlrev_b32_e32 v44, 16, v57
	v_and_b32_e32 v43, 0xffff0000, v53
	v_and_b32_e32 v45, 0xffff0000, v57
	v_lshlrev_b32_e32 v52, 16, v54
	v_lshlrev_b32_e32 v56, 16, v58
	v_and_b32_e32 v53, 0xffff0000, v54
	v_and_b32_e32 v57, 0xffff0000, v58
	v_lshlrev_b32_e32 v54, 16, v55
	v_lshlrev_b32_e32 v58, 16, v59
	v_and_b32_e32 v59, 0xffff0000, v59
	v_and_b32_e32 v55, 0xffff0000, v55
	v_pk_mul_f32 v[38:39], v[38:39], v[40:41]
	v_pk_mul_f32 v[40:41], v[42:43], v[44:45]
	v_pk_mul_f32 v[42:43], v[52:53], v[56:57]
	v_pk_mul_f32 v[44:45], v[54:55], v[58:59]
	v_lshlrev_b32_e32 v74, 16, v60
	v_and_b32_e32 v75, 0xffff0000, v60
	v_lshlrev_b32_e32 v60, 16, v61
	v_and_b32_e32 v61, 0xffff0000, v61
	v_lshlrev_b32_e32 v76, 16, v62
	v_and_b32_e32 v77, 0xffff0000, v62
	v_lshlrev_b32_e32 v62, 16, v63
	v_and_b32_e32 v63, 0xffff0000, v63
	v_pk_fma_f32 v[52:53], v[12:13], v[38:39], v[64:65]
	v_pk_fma_f32 v[54:55], v[14:15], v[40:41], v[66:67]
	v_pk_fma_f32 v[56:57], v[20:21], v[42:43], v[68:69]
	v_pk_fma_f32 v[58:59], v[22:23], v[44:45], v[70:71]
	v_pk_mul_f32 v[52:53], v[52:53], v[74:75]
	v_pk_mul_f32 v[54:55], v[54:55], v[60:61]
	v_pk_mul_f32 v[56:57], v[56:57], v[76:77]
	v_pk_mul_f32 v[58:59], v[58:59], v[62:63]
	v_cvt_pk_bf16_f32 v52, v52, v53
	v_cvt_pk_bf16_f32 v53, v54, v55
	v_cvt_pk_bf16_f32 v54, v56, v57
	v_cvt_pk_bf16_f32 v55, v58, v59
	global_store_dwordx4 v[72:73], v[52:55], off
	v_pk_mul_f32 v[64:65], v[8:9], v[38:39]
	v_pk_mul_f32 v[66:67], v[10:11], v[40:41]
	v_pk_mul_f32 v[68:69], v[16:17], v[42:43]
	v_pk_mul_f32 v[70:71], v[18:19], v[44:45]
	v_pk_fma_f32 v[64:65], v[4:5], v[26:27], v[64:65]
	v_pk_fma_f32 v[66:67], v[6:7], v[28:29], v[66:67]
	v_pk_fma_f32 v[68:69], v[0:1], v[30:31], v[68:69]
	v_pk_fma_f32 v[70:71], v[2:3], v[32:33], v[70:71]
	v_mov_b32_e32 v26, v38
	v_mov_b32_e32 v27, v39
	v_mov_b32_e32 v28, v40
	v_mov_b32_e32 v29, v41
	v_mov_b32_e32 v30, v42
	v_mov_b32_e32 v31, v43
	v_mov_b32_e32 v32, v44
	v_mov_b32_e32 v33, v45
	v_and_or_b32 v24, v49, s28, v47
	v_and_b32_e32 v51, 32, v50
	v_bitop3_b32 v24, v24, v48, v51 bitop3:0xde
	v_add_u32_e32 v50, 4, v50
	v_add_u32_e32 v49, 64, v49
	v_lshl_add_u64 v[72:73], v[34:35], 0, v[24:25]
	s_waitcnt vmcnt(5)
; __device__ __forceinline__ float bf_lo(u32 v) { return __uint_as_float(v << 16); }
; __device__ __forceinline__ float bf_hi(u32 v) { return __uint_as_float(v & 0xFFFF0000u); }
; __device__ __forceinline__ void mixer_phase(const Params& p, char* shm) {
;     ...
;       for (int r = 0; r < 16; ++r) {
;         const u16* zr = z + (size_t)(row0 + r) * DIN;
;         uint4 gb = *(const uint4*)(zr + 2048 + c0);
;         uint4 gc = *(const uint4*)(zr + 3072 + c0);
;         uint4 xt = *(const uint4*)(zr + 4096 + c0);
;         float hh[8], gbf[8], y[8];
;         hh[0] = bf_lo(gc.x) * bf_lo(xt.x); hh[1] = bf_hi(gc.x) * bf_hi(xt.x);
;         hh[2] = bf_lo(gc.y) * bf_lo(xt.y); hh[3] = bf_hi(gc.y) * bf_hi(xt.y);
;         hh[4] = bf_lo(gc.z) * bf_lo(xt.z); hh[5] = bf_hi(gc.z) * bf_hi(xt.z);
;         hh[6] = bf_lo(gc.w) * bf_lo(xt.w); hh[7] = bf_hi(gc.w) * bf_hi(xt.w);
;         gbf[0] = bf_lo(gb.x); gbf[1] = bf_hi(gb.x); gbf[2] = bf_lo(gb.y); gbf[3] = bf_hi(gb.y);
;         gbf[4] = bf_lo(gb.z); gbf[5] = bf_hi(gb.z); gbf[6] = bf_lo(gb.w); gbf[7] = bf_hi(gb.w);
; #pragma unroll
;         for (int e = 0; e < 8; ++e) {
;           y[e] = gbf[e] * (w0[e] * h2[e] + w1[e] * h1[e] + w2[e] * hh[e]);
;           h2[e] = h1[e]; h1[e] = hh[e];
;         }
;         uint4 o;
;         o.x = pack2(y[0], y[1]); o.y = pack2(y[2], y[3]); o.z = pack2(y[4], y[5]); o.w = pack2(y[6], y[7]);
;         *(uint4*)((char*)ymix + tl_off(row0 + r, DA + c0, DM >> 6)) = o;
;       }
	v_mov_b32_e32 v52, v96
	v_mov_b32_e32 v53, v97
	v_mov_b32_e32 v54, v98
	v_mov_b32_e32 v55, v99
	v_mov_b32_e32 v56, v100
	v_mov_b32_e32 v57, v101
	v_mov_b32_e32 v58, v102
	v_mov_b32_e32 v59, v103
	v_mov_b32_e32 v60, v104
	v_mov_b32_e32 v61, v105
	v_mov_b32_e32 v62, v106
	v_mov_b32_e32 v63, v107
	v_lshl_add_u64 v[112:113], v[36:37], 0, s[10:11]
	v_add_co_u32_e32 v114, vcc, s26, v112
	s_nop 1
	v_addc_co_u32_e32 v115, vcc, 0, v113, vcc
	v_add_co_u32_e32 v116, vcc, s27, v112
	s_nop 1
	v_addc_co_u32_e32 v117, vcc, 0, v113, vcc
	global_load_dwordx4 v[96:99], v[114:115], off offset:2048
	global_load_dwordx4 v[100:103], v[116:117], off
	global_load_dwordx4 v[104:107], v[116:117], off offset:-4096
	s_add_u32 s10, s10, 0x2800
	s_addc_u32 s11, s11, 0
	v_lshlrev_b32_e32 v38, 16, v52
	v_lshlrev_b32_e32 v40, 16, v56
	v_and_b32_e32 v39, 0xffff0000, v52
	v_and_b32_e32 v41, 0xffff0000, v56
	v_lshlrev_b32_e32 v42, 16, v53
	v_lshlrev_b32_e32 v44, 16, v57
	v_and_b32_e32 v43, 0xffff0000, v53
	v_and_b32_e32 v45, 0xffff0000, v57
	v_lshlrev_b32_e32 v52, 16, v54
	v_lshlrev_b32_e32 v56, 16, v58
	v_and_b32_e32 v53, 0xffff0000, v54
	v_and_b32_e32 v57, 0xffff0000, v58
	v_lshlrev_b32_e32 v54, 16, v55
	v_lshlrev_b32_e32 v58, 16, v59
	v_and_b32_e32 v59, 0xffff0000, v59
	v_and_b32_e32 v55, 0xffff0000, v55
	v_pk_mul_f32 v[38:39], v[38:39], v[40:41]
	v_pk_mul_f32 v[40:41], v[42:43], v[44:45]
	v_pk_mul_f32 v[42:43], v[52:53], v[56:57]
	v_pk_mul_f32 v[44:45], v[54:55], v[58:59]
	v_lshlrev_b32_e32 v74, 16, v60
	v_and_b32_e32 v75, 0xffff0000, v60
	v_lshlrev_b32_e32 v60, 16, v61
	v_and_b32_e32 v61, 0xffff0000, v61
	v_lshlrev_b32_e32 v76, 16, v62
	v_and_b32_e32 v77, 0xffff0000, v62
	v_lshlrev_b32_e32 v62, 16, v63
	v_and_b32_e32 v63, 0xffff0000, v63
	v_pk_fma_f32 v[52:53], v[12:13], v[38:39], v[64:65]
	v_pk_fma_f32 v[54:55], v[14:15], v[40:41], v[66:67]
	v_pk_fma_f32 v[56:57], v[20:21], v[42:43], v[68:69]
	v_pk_fma_f32 v[58:59], v[22:23], v[44:45], v[70:71]
	v_pk_mul_f32 v[52:53], v[52:53], v[74:75]
	v_pk_mul_f32 v[54:55], v[54:55], v[60:61]
	v_pk_mul_f32 v[56:57], v[56:57], v[76:77]
	v_pk_mul_f32 v[58:59], v[58:59], v[62:63]
	v_cvt_pk_bf16_f32 v52, v52, v53
	v_cvt_pk_bf16_f32 v53, v54, v55
	v_cvt_pk_bf16_f32 v54, v56, v57
	v_cvt_pk_bf16_f32 v55, v58, v59
	global_store_dwordx4 v[72:73], v[52:55], off
	v_pk_mul_f32 v[64:65], v[8:9], v[38:39]
	v_pk_mul_f32 v[66:67], v[10:11], v[40:41]
	v_pk_mul_f32 v[68:69], v[16:17], v[42:43]
	v_pk_mul_f32 v[70:71], v[18:19], v[44:45]
	v_pk_fma_f32 v[64:65], v[4:5], v[26:27], v[64:65]
	v_pk_fma_f32 v[66:67], v[6:7], v[28:29], v[66:67]
	v_pk_fma_f32 v[68:69], v[0:1], v[30:31], v[68:69]
	v_pk_fma_f32 v[70:71], v[2:3], v[32:33], v[70:71]
	v_mov_b32_e32 v26, v38
	v_mov_b32_e32 v27, v39
	v_mov_b32_e32 v28, v40
	v_mov_b32_e32 v29, v41
	v_mov_b32_e32 v30, v42
	v_mov_b32_e32 v31, v43
	v_mov_b32_e32 v32, v44
	v_mov_b32_e32 v33, v45
	v_and_or_b32 v24, v49, s28, v47
	v_and_b32_e32 v51, 32, v50
	v_bitop3_b32 v24, v24, v48, v51 bitop3:0xde
	v_add_u32_e32 v50, 4, v50
	v_add_u32_e32 v49, 64, v49
	v_lshl_add_u64 v[72:73], v[34:35], 0, v[24:25]
	s_waitcnt vmcnt(5)
	v_mov_b32_e32 v52, v80
	v_mov_b32_e32 v53, v81
	v_mov_b32_e32 v54, v82
	v_mov_b32_e32 v55, v83
	v_mov_b32_e32 v56, v84
	v_mov_b32_e32 v57, v85
	v_mov_b32_e32 v58, v86
	v_mov_b32_e32 v59, v87
	v_mov_b32_e32 v60, v88
	v_mov_b32_e32 v61, v89
	v_mov_b32_e32 v62, v90
	v_mov_b32_e32 v63, v91
	v_lshl_add_u64 v[112:113], v[36:37], 0, s[10:11]
	v_add_co_u32_e32 v114, vcc, s26, v112
	s_nop 1
	v_addc_co_u32_e32 v115, vcc, 0, v113, vcc
	v_add_co_u32_e32 v116, vcc, s27, v112
	s_nop 1
	v_addc_co_u32_e32 v117, vcc, 0, v113, vcc
	global_load_dwordx4 v[80:83], v[114:115], off offset:2048
	global_load_dwordx4 v[84:87], v[116:117], off
	global_load_dwordx4 v[88:91], v[116:117], off offset:-4096
	s_add_u32 s10, s10, 0x2800
	s_addc_u32 s11, s11, 0
	v_lshlrev_b32_e32 v38, 16, v52
	v_lshlrev_b32_e32 v40, 16, v56
	v_and_b32_e32 v39, 0xffff0000, v52
	v_and_b32_e32 v41, 0xffff0000, v56
	v_lshlrev_b32_e32 v42, 16, v53
	v_lshlrev_b32_e32 v44, 16, v57
	v_and_b32_e32 v43, 0xffff0000, v53
	v_and_b32_e32 v45, 0xffff0000, v57
	v_lshlrev_b32_e32 v52, 16, v54
	v_lshlrev_b32_e32 v56, 16, v58
	v_and_b32_e32 v53, 0xffff0000, v54
	v_and_b32_e32 v57, 0xffff0000, v58
	v_lshlrev_b32_e32 v54, 16, v55
	v_lshlrev_b32_e32 v58, 16, v59
	v_and_b32_e32 v59, 0xffff0000, v59
	v_and_b32_e32 v55, 0xffff0000, v55
	v_pk_mul_f32 v[38:39], v[38:39], v[40:41]
	v_pk_mul_f32 v[40:41], v[42:43], v[44:45]
	v_pk_mul_f32 v[42:43], v[52:53], v[56:57]
	v_pk_mul_f32 v[44:45], v[54:55], v[58:59]
	v_lshlrev_b32_e32 v74, 16, v60
	v_and_b32_e32 v75, 0xffff0000, v60
	v_lshlrev_b32_e32 v60, 16, v61
	v_and_b32_e32 v61, 0xffff0000, v61
	v_lshlrev_b32_e32 v76, 16, v62
	v_and_b32_e32 v77, 0xffff0000, v62
	v_lshlrev_b32_e32 v62, 16, v63
	v_and_b32_e32 v63, 0xffff0000, v63
	v_pk_fma_f32 v[52:53], v[12:13], v[38:39], v[64:65]
	v_pk_fma_f32 v[54:55], v[14:15], v[40:41], v[66:67]
	v_pk_fma_f32 v[56:57], v[20:21], v[42:43], v[68:69]
	v_pk_fma_f32 v[58:59], v[22:23], v[44:45], v[70:71]
	v_pk_mul_f32 v[52:53], v[52:53], v[74:75]
	v_pk_mul_f32 v[54:55], v[54:55], v[60:61]
	v_pk_mul_f32 v[56:57], v[56:57], v[76:77]
	v_pk_mul_f32 v[58:59], v[58:59], v[62:63]
	v_cvt_pk_bf16_f32 v52, v52, v53
	v_cvt_pk_bf16_f32 v53, v54, v55
	v_cvt_pk_bf16_f32 v54, v56, v57
	v_cvt_pk_bf16_f32 v55, v58, v59
	global_store_dwordx4 v[72:73], v[52:55], off
	v_pk_mul_f32 v[64:65], v[8:9], v[38:39]
	v_pk_mul_f32 v[66:67], v[10:11], v[40:41]
	v_pk_mul_f32 v[68:69], v[16:17], v[42:43]
	v_pk_mul_f32 v[70:71], v[18:19], v[44:45]
	v_pk_fma_f32 v[64:65], v[4:5], v[26:27], v[64:65]
	v_pk_fma_f32 v[66:67], v[6:7], v[28:29], v[66:67]
	v_pk_fma_f32 v[68:69], v[0:1], v[30:31], v[68:69]
	v_pk_fma_f32 v[70:71], v[2:3], v[32:33], v[70:71]
	v_mov_b32_e32 v26, v38
	v_mov_b32_e32 v27, v39
	v_mov_b32_e32 v28, v40
	v_mov_b32_e32 v29, v41
	v_mov_b32_e32 v30, v42
	v_mov_b32_e32 v31, v43
	v_mov_b32_e32 v32, v44
	v_mov_b32_e32 v33, v45
	v_and_or_b32 v24, v49, s28, v47
	v_and_b32_e32 v51, 32, v50
	v_bitop3_b32 v24, v24, v48, v51 bitop3:0xde
	v_add_u32_e32 v50, 4, v50
	v_add_u32_e32 v49, 64, v49
	v_lshl_add_u64 v[72:73], v[34:35], 0, v[24:25]
	s_waitcnt vmcnt(5)
; __device__ __forceinline__ float bf_lo(u32 v) { return __uint_as_float(v << 16); }
; __device__ __forceinline__ float bf_hi(u32 v) { return __uint_as_float(v & 0xFFFF0000u); }
; __device__ __forceinline__ void mixer_phase(const Params& p, char* shm) {
;     ...
;       for (int r = 0; r < 16; ++r) {
;         const u16* zr = z + (size_t)(row0 + r) * DIN;
;         uint4 gb = *(const uint4*)(zr + 2048 + c0);
;         uint4 gc = *(const uint4*)(zr + 3072 + c0);
;         uint4 xt = *(const uint4*)(zr + 4096 + c0);
;         float hh[8], gbf[8], y[8];
;         hh[0] = bf_lo(gc.x) * bf_lo(xt.x); hh[1] = bf_hi(gc.x) * bf_hi(xt.x);
;         hh[2] = bf_lo(gc.y) * bf_lo(xt.y); hh[3] = bf_hi(gc.y) * bf_hi(xt.y);
;         hh[4] = bf_lo(gc.z) * bf_lo(xt.z); hh[5] = bf_hi(gc.z) * bf_hi(xt.z);
;         hh[6] = bf_lo(gc.w) * bf_lo(xt.w); hh[7] = bf_hi(gc.w) * bf_hi(xt.w);
;         gbf[0] = bf_lo(gb.x); gbf[1] = bf_hi(gb.x); gbf[2] = bf_lo(gb.y); gbf[3] = bf_hi(gb.y);
;         gbf[4] = bf_lo(gb.z); gbf[5] = bf_hi(gb.z); gbf[6] = bf_lo(gb.w); gbf[7] = bf_hi(gb.w);
; #pragma unroll
;         for (int e = 0; e < 8; ++e) {
;           y[e] = gbf[e] * (w0[e] * h2[e] + w1[e] * h1[e] + w2[e] * hh[e]);
;           h2[e] = h1[e]; h1[e] = hh[e];
;         }
;         uint4 o;
;         o.x = pack2(y[0], y[1]); o.y = pack2(y[2], y[3]); o.z = pack2(y[4], y[5]); o.w = pack2(y[6], y[7]);
;         *(uint4*)((char*)ymix + tl_off(row0 + r, DA + c0, DM >> 6)) = o;
;       }
	v_mov_b32_e32 v52, v96
	v_mov_b32_e32 v53, v97
	v_mov_b32_e32 v54, v98
	v_mov_b32_e32 v55, v99
	v_mov_b32_e32 v56, v100
	v_mov_b32_e32 v57, v101
	v_mov_b32_e32 v58, v102
	v_mov_b32_e32 v59, v103
	v_mov_b32_e32 v60, v104
	v_mov_b32_e32 v61, v105
	v_mov_b32_e32 v62, v106
	v_mov_b32_e32 v63, v107
	v_lshl_add_u64 v[112:113], v[36:37], 0, s[10:11]
	v_add_co_u32_e32 v114, vcc, s26, v112
	s_nop 1
	v_addc_co_u32_e32 v115, vcc, 0, v113, vcc
	v_add_co_u32_e32 v116, vcc, s27, v112
	s_nop 1
	v_addc_co_u32_e32 v117, vcc, 0, v113, vcc
	global_load_dwordx4 v[96:99], v[114:115], off offset:2048
	global_load_dwordx4 v[100:103], v[116:117], off
	global_load_dwordx4 v[104:107], v[116:117], off offset:-4096
	s_add_u32 s10, s10, 0x2800
	s_addc_u32 s11, s11, 0
	v_lshlrev_b32_e32 v38, 16, v52
	v_lshlrev_b32_e32 v40, 16, v56
	v_and_b32_e32 v39, 0xffff0000, v52
	v_and_b32_e32 v41, 0xffff0000, v56
	v_lshlrev_b32_e32 v42, 16, v53
	v_lshlrev_b32_e32 v44, 16, v57
	v_and_b32_e32 v43, 0xffff0000, v53
	v_and_b32_e32 v45, 0xffff0000, v57
	v_lshlrev_b32_e32 v52, 16, v54
	v_lshlrev_b32_e32 v56, 16, v58
	v_and_b32_e32 v53, 0xffff0000, v54
	v_and_b32_e32 v57, 0xffff0000, v58
	v_lshlrev_b32_e32 v54, 16, v55
	v_lshlrev_b32_e32 v58, 16, v59
	v_and_b32_e32 v59, 0xffff0000, v59
	v_and_b32_e32 v55, 0xffff0000, v55
	v_pk_mul_f32 v[38:39], v[38:39], v[40:41]
	v_pk_mul_f32 v[40:41], v[42:43], v[44:45]
	v_pk_mul_f32 v[42:43], v[52:53], v[56:57]
	v_pk_mul_f32 v[44:45], v[54:55], v[58:59]
	v_lshlrev_b32_e32 v74, 16, v60
	v_and_b32_e32 v75, 0xffff0000, v60
	v_lshlrev_b32_e32 v60, 16, v61
	v_and_b32_e32 v61, 0xffff0000, v61
	v_lshlrev_b32_e32 v76, 16, v62
	v_and_b32_e32 v77, 0xffff0000, v62
	v_lshlrev_b32_e32 v62, 16, v63
	v_and_b32_e32 v63, 0xffff0000, v63
	v_pk_fma_f32 v[52:53], v[12:13], v[38:39], v[64:65]
	v_pk_fma_f32 v[54:55], v[14:15], v[40:41], v[66:67]
	v_pk_fma_f32 v[56:57], v[20:21], v[42:43], v[68:69]
	v_pk_fma_f32 v[58:59], v[22:23], v[44:45], v[70:71]
	v_pk_mul_f32 v[52:53], v[52:53], v[74:75]
	v_pk_mul_f32 v[54:55], v[54:55], v[60:61]
	v_pk_mul_f32 v[56:57], v[56:57], v[76:77]
	v_pk_mul_f32 v[58:59], v[58:59], v[62:63]
	v_cvt_pk_bf16_f32 v52, v52, v53
	v_cvt_pk_bf16_f32 v53, v54, v55
	v_cvt_pk_bf16_f32 v54, v56, v57
	v_cvt_pk_bf16_f32 v55, v58, v59
	global_store_dwordx4 v[72:73], v[52:55], off
	v_pk_mul_f32 v[64:65], v[8:9], v[38:39]
	v_pk_mul_f32 v[66:67], v[10:11], v[40:41]
	v_pk_mul_f32 v[68:69], v[16:17], v[42:43]
	v_pk_mul_f32 v[70:71], v[18:19], v[44:45]
	v_pk_fma_f32 v[64:65], v[4:5], v[26:27], v[64:65]
	v_pk_fma_f32 v[66:67], v[6:7], v[28:29], v[66:67]
	v_pk_fma_f32 v[68:69], v[0:1], v[30:31], v[68:69]
	v_pk_fma_f32 v[70:71], v[2:3], v[32:33], v[70:71]
	v_mov_b32_e32 v26, v38
	v_mov_b32_e32 v27, v39
	v_mov_b32_e32 v28, v40
	v_mov_b32_e32 v29, v41
	v_mov_b32_e32 v30, v42
	v_mov_b32_e32 v31, v43
	v_mov_b32_e32 v32, v44
	v_mov_b32_e32 v33, v45
	v_and_or_b32 v24, v49, s28, v47
	v_and_b32_e32 v51, 32, v50
	v_bitop3_b32 v24, v24, v48, v51 bitop3:0xde
	v_add_u32_e32 v50, 4, v50
	v_add_u32_e32 v49, 64, v49
	v_lshl_add_u64 v[72:73], v[34:35], 0, v[24:25]
	s_waitcnt vmcnt(5)
	v_mov_b32_e32 v52, v80
	v_mov_b32_e32 v53, v81
	v_mov_b32_e32 v54, v82
	v_mov_b32_e32 v55, v83
	v_mov_b32_e32 v56, v84
	v_mov_b32_e32 v57, v85
	v_mov_b32_e32 v58, v86
	v_mov_b32_e32 v59, v87
	v_mov_b32_e32 v60, v88
	v_mov_b32_e32 v61, v89
	v_mov_b32_e32 v62, v90
	v_mov_b32_e32 v63, v91
	v_lshl_add_u64 v[112:113], v[36:37], 0, s[10:11]
	v_add_co_u32_e32 v114, vcc, s26, v112
	s_nop 1
	v_addc_co_u32_e32 v115, vcc, 0, v113, vcc
	v_add_co_u32_e32 v116, vcc, s27, v112
	s_nop 1
	v_addc_co_u32_e32 v117, vcc, 0, v113, vcc
	global_load_dwordx4 v[80:83], v[114:115], off offset:2048
	global_load_dwordx4 v[84:87], v[116:117], off
	global_load_dwordx4 v[88:91], v[116:117], off offset:-4096
	s_add_u32 s10, s10, 0x2800
	s_addc_u32 s11, s11, 0
	v_lshlrev_b32_e32 v38, 16, v52
	v_lshlrev_b32_e32 v40, 16, v56
	v_and_b32_e32 v39, 0xffff0000, v52
	v_and_b32_e32 v41, 0xffff0000, v56
	v_lshlrev_b32_e32 v42, 16, v53
	v_lshlrev_b32_e32 v44, 16, v57
	v_and_b32_e32 v43, 0xffff0000, v53
	v_and_b32_e32 v45, 0xffff0000, v57
	v_lshlrev_b32_e32 v52, 16, v54
	v_lshlrev_b32_e32 v56, 16, v58
	v_and_b32_e32 v53, 0xffff0000, v54
	v_and_b32_e32 v57, 0xffff0000, v58
	v_lshlrev_b32_e32 v54, 16, v55
	v_lshlrev_b32_e32 v58, 16, v59
	v_and_b32_e32 v59, 0xffff0000, v59
	v_and_b32_e32 v55, 0xffff0000, v55
	v_pk_mul_f32 v[38:39], v[38:39], v[40:41]
	v_pk_mul_f32 v[40:41], v[42:43], v[44:45]
	v_pk_mul_f32 v[42:43], v[52:53], v[56:57]
	v_pk_mul_f32 v[44:45], v[54:55], v[58:59]
	v_lshlrev_b32_e32 v74, 16, v60
	v_and_b32_e32 v75, 0xffff0000, v60
	v_lshlrev_b32_e32 v60, 16, v61
	v_and_b32_e32 v61, 0xffff0000, v61
	v_lshlrev_b32_e32 v76, 16, v62
	v_and_b32_e32 v77, 0xffff0000, v62
	v_lshlrev_b32_e32 v62, 16, v63
	v_and_b32_e32 v63, 0xffff0000, v63
	v_pk_fma_f32 v[52:53], v[12:13], v[38:39], v[64:65]
	v_pk_fma_f32 v[54:55], v[14:15], v[40:41], v[66:67]
	v_pk_fma_f32 v[56:57], v[20:21], v[42:43], v[68:69]
	v_pk_fma_f32 v[58:59], v[22:23], v[44:45], v[70:71]
	v_pk_mul_f32 v[52:53], v[52:53], v[74:75]
	v_pk_mul_f32 v[54:55], v[54:55], v[60:61]
	v_pk_mul_f32 v[56:57], v[56:57], v[76:77]
	v_pk_mul_f32 v[58:59], v[58:59], v[62:63]
	v_cvt_pk_bf16_f32 v52, v52, v53
	v_cvt_pk_bf16_f32 v53, v54, v55
	v_cvt_pk_bf16_f32 v54, v56, v57
	v_cvt_pk_bf16_f32 v55, v58, v59
	global_store_dwordx4 v[72:73], v[52:55], off
	v_pk_mul_f32 v[64:65], v[8:9], v[38:39]
	v_pk_mul_f32 v[66:67], v[10:11], v[40:41]
	v_pk_mul_f32 v[68:69], v[16:17], v[42:43]
	v_pk_mul_f32 v[70:71], v[18:19], v[44:45]
	v_pk_fma_f32 v[64:65], v[4:5], v[26:27], v[64:65]
	v_pk_fma_f32 v[66:67], v[6:7], v[28:29], v[66:67]
	v_pk_fma_f32 v[68:69], v[0:1], v[30:31], v[68:69]
	v_pk_fma_f32 v[70:71], v[2:3], v[32:33], v[70:71]
	v_mov_b32_e32 v26, v38
	v_mov_b32_e32 v27, v39
	v_mov_b32_e32 v28, v40
	v_mov_b32_e32 v29, v41
	v_mov_b32_e32 v30, v42
	v_mov_b32_e32 v31, v43
	v_mov_b32_e32 v32, v44
	v_mov_b32_e32 v33, v45
	v_and_or_b32 v24, v49, s28, v47
	v_and_b32_e32 v51, 32, v50
	v_bitop3_b32 v24, v24, v48, v51 bitop3:0xde
	v_add_u32_e32 v50, 4, v50
	v_add_u32_e32 v49, 64, v49
	v_lshl_add_u64 v[72:73], v[34:35], 0, v[24:25]
	s_waitcnt vmcnt(5)
; __device__ __forceinline__ float bf_lo(u32 v) { return __uint_as_float(v << 16); }
; __device__ __forceinline__ float bf_hi(u32 v) { return __uint_as_float(v & 0xFFFF0000u); }
; __device__ __forceinline__ void mixer_phase(const Params& p, char* shm) {
;     ...
;       for (int r = 0; r < 16; ++r) {
;         const u16* zr = z + (size_t)(row0 + r) * DIN;
;         uint4 gb = *(const uint4*)(zr + 2048 + c0);
;         uint4 gc = *(const uint4*)(zr + 3072 + c0);
;         uint4 xt = *(const uint4*)(zr + 4096 + c0);
;         float hh[8], gbf[8], y[8];
;         hh[0] = bf_lo(gc.x) * bf_lo(xt.x); hh[1] = bf_hi(gc.x) * bf_hi(xt.x);
;         hh[2] = bf_lo(gc.y) * bf_lo(xt.y); hh[3] = bf_hi(gc.y) * bf_hi(xt.y);
;         hh[4] = bf_lo(gc.z) * bf_lo(xt.z); hh[5] = bf_hi(gc.z) * bf_hi(xt.z);
;         hh[6] = bf_lo(gc.w) * bf_lo(xt.w); hh[7] = bf_hi(gc.w) * bf_hi(xt.w);
;         gbf[0] = bf_lo(gb.x); gbf[1] = bf_hi(gb.x); gbf[2] = bf_lo(gb.y); gbf[3] = bf_hi(gb.y);
;         gbf[4] = bf_lo(gb.z); gbf[5] = bf_hi(gb.z); gbf[6] = bf_lo(gb.w); gbf[7] = bf_hi(gb.w);
; #pragma unroll
;         for (int e = 0; e < 8; ++e) {
;           y[e] = gbf[e] * (w0[e] * h2[e] + w1[e] * h1[e] + w2[e] * hh[e]);
;           h2[e] = h1[e]; h1[e] = hh[e];
;         }
;         uint4 o;
;         o.x = pack2(y[0], y[1]); o.y = pack2(y[2], y[3]); o.z = pack2(y[4], y[5]); o.w = pack2(y[6], y[7]);
;         *(uint4*)((char*)ymix + tl_off(row0 + r, DA + c0, DM >> 6)) = o;
;       }
	v_mov_b32_e32 v52, v96
	v_mov_b32_e32 v53, v97
	v_mov_b32_e32 v54, v98
	v_mov_b32_e32 v55, v99
	v_mov_b32_e32 v56, v100
	v_mov_b32_e32 v57, v101
	v_mov_b32_e32 v58, v102
	v_mov_b32_e32 v59, v103
	v_mov_b32_e32 v60, v104
	v_mov_b32_e32 v61, v105
	v_mov_b32_e32 v62, v106
	v_mov_b32_e32 v63, v107
	v_lshl_add_u64 v[112:113], v[36:37], 0, s[10:11]
	v_add_co_u32_e32 v114, vcc, s26, v112
	s_nop 1
	v_addc_co_u32_e32 v115, vcc, 0, v113, vcc
	v_add_co_u32_e32 v116, vcc, s27, v112
	s_nop 1
	v_addc_co_u32_e32 v117, vcc, 0, v113, vcc
	global_load_dwordx4 v[96:99], v[114:115], off offset:2048
	global_load_dwordx4 v[100:103], v[116:117], off
	global_load_dwordx4 v[104:107], v[116:117], off offset:-4096
	s_add_u32 s10, s10, 0x2800
	s_addc_u32 s11, s11, 0
	v_lshlrev_b32_e32 v38, 16, v52
	v_lshlrev_b32_e32 v40, 16, v56
	v_and_b32_e32 v39, 0xffff0000, v52
	v_and_b32_e32 v41, 0xffff0000, v56
	v_lshlrev_b32_e32 v42, 16, v53
	v_lshlrev_b32_e32 v44, 16, v57
	v_and_b32_e32 v43, 0xffff0000, v53
	v_and_b32_e32 v45, 0xffff0000, v57
	v_lshlrev_b32_e32 v52, 16, v54
	v_lshlrev_b32_e32 v56, 16, v58
	v_and_b32_e32 v53, 0xffff0000, v54
	v_and_b32_e32 v57, 0xffff0000, v58
	v_lshlrev_b32_e32 v54, 16, v55
	v_lshlrev_b32_e32 v58, 16, v59
	v_and_b32_e32 v59, 0xffff0000, v59
	v_and_b32_e32 v55, 0xffff0000, v55
	v_pk_mul_f32 v[38:39], v[38:39], v[40:41]
	v_pk_mul_f32 v[40:41], v[42:43], v[44:45]
	v_pk_mul_f32 v[42:43], v[52:53], v[56:57]
	v_pk_mul_f32 v[44:45], v[54:55], v[58:59]
	v_lshlrev_b32_e32 v74, 16, v60
	v_and_b32_e32 v75, 0xffff0000, v60
	v_lshlrev_b32_e32 v60, 16, v61
	v_and_b32_e32 v61, 0xffff0000, v61
	v_lshlrev_b32_e32 v76, 16, v62
	v_and_b32_e32 v77, 0xffff0000, v62
	v_lshlrev_b32_e32 v62, 16, v63
	v_and_b32_e32 v63, 0xffff0000, v63
	v_pk_fma_f32 v[52:53], v[12:13], v[38:39], v[64:65]
	v_pk_fma_f32 v[54:55], v[14:15], v[40:41], v[66:67]
	v_pk_fma_f32 v[56:57], v[20:21], v[42:43], v[68:69]
	v_pk_fma_f32 v[58:59], v[22:23], v[44:45], v[70:71]
	v_pk_mul_f32 v[52:53], v[52:53], v[74:75]
	v_pk_mul_f32 v[54:55], v[54:55], v[60:61]
	v_pk_mul_f32 v[56:57], v[56:57], v[76:77]
	v_pk_mul_f32 v[58:59], v[58:59], v[62:63]
	v_cvt_pk_bf16_f32 v52, v52, v53
	v_cvt_pk_bf16_f32 v53, v54, v55
	v_cvt_pk_bf16_f32 v54, v56, v57
	v_cvt_pk_bf16_f32 v55, v58, v59
	global_store_dwordx4 v[72:73], v[52:55], off
	v_pk_mul_f32 v[64:65], v[8:9], v[38:39]
	v_pk_mul_f32 v[66:67], v[10:11], v[40:41]
	v_pk_mul_f32 v[68:69], v[16:17], v[42:43]
	v_pk_mul_f32 v[70:71], v[18:19], v[44:45]
	v_pk_fma_f32 v[64:65], v[4:5], v[26:27], v[64:65]
	v_pk_fma_f32 v[66:67], v[6:7], v[28:29], v[66:67]
	v_pk_fma_f32 v[68:69], v[0:1], v[30:31], v[68:69]
	v_pk_fma_f32 v[70:71], v[2:3], v[32:33], v[70:71]
	v_mov_b32_e32 v26, v38
	v_mov_b32_e32 v27, v39
	v_mov_b32_e32 v28, v40
	v_mov_b32_e32 v29, v41
	v_mov_b32_e32 v30, v42
	v_mov_b32_e32 v31, v43
	v_mov_b32_e32 v32, v44
	v_mov_b32_e32 v33, v45
	v_and_or_b32 v24, v49, s28, v47
	v_and_b32_e32 v51, 32, v50
	v_bitop3_b32 v24, v24, v48, v51 bitop3:0xde
	v_add_u32_e32 v50, 4, v50
	v_add_u32_e32 v49, 64, v49
	v_lshl_add_u64 v[72:73], v[34:35], 0, v[24:25]
	s_waitcnt vmcnt(5)
; __device__ __forceinline__ float bf_lo(u32 v) { return __uint_as_float(v << 16); }
; __device__ __forceinline__ float bf_hi(u32 v) { return __uint_as_float(v & 0xFFFF0000u); }
; __device__ __forceinline__ void mixer_phase(const Params& p, char* shm) {
;     ...
;       for (int r = 0; r < 16; ++r) {
;         const u16* zr = z + (size_t)(row0 + r) * DIN;
;         uint4 gb = *(const uint4*)(zr + 2048 + c0);
;         uint4 gc = *(const uint4*)(zr + 3072 + c0);
;         uint4 xt = *(const uint4*)(zr + 4096 + c0);
;         float hh[8], gbf[8], y[8];
;         hh[0] = bf_lo(gc.x) * bf_lo(xt.x); hh[1] = bf_hi(gc.x) * bf_hi(xt.x);
;         hh[2] = bf_lo(gc.y) * bf_lo(xt.y); hh[3] = bf_hi(gc.y) * bf_hi(xt.y);
;         hh[4] = bf_lo(gc.z) * bf_lo(xt.z); hh[5] = bf_hi(gc.z) * bf_hi(xt.z);
;         hh[6] = bf_lo(gc.w) * bf_lo(xt.w); hh[7] = bf_hi(gc.w) * bf_hi(xt.w);
;         gbf[0] = bf_lo(gb.x); gbf[1] = bf_hi(gb.x); gbf[2] = bf_lo(gb.y); gbf[3] = bf_hi(gb.y);
;         gbf[4] = bf_lo(gb.z); gbf[5] = bf_hi(gb.z); gbf[6] = bf_lo(gb.w); gbf[7] = bf_hi(gb.w);
; #pragma unroll
;         for (int e = 0; e < 8; ++e) {
;           y[e] = gbf[e] * (w0[e] * h2[e] + w1[e] * h1[e] + w2[e] * hh[e]);
;           h2[e] = h1[e]; h1[e] = hh[e];
;         }
;         uint4 o;
;         o.x = pack2(y[0], y[1]); o.y = pack2(y[2], y[3]); o.z = pack2(y[4], y[5]); o.w = pack2(y[6], y[7]);
;         *(uint4*)((char*)ymix + tl_off(row0 + r, DA + c0, DM >> 6)) = o;
;       }
	v_mov_b32_e32 v52, v80
	v_mov_b32_e32 v53, v81
	v_mov_b32_e32 v54, v82
	v_mov_b32_e32 v55, v83
	v_mov_b32_e32 v56, v84
	v_mov_b32_e32 v57, v85
	v_mov_b32_e32 v58, v86
	v_mov_b32_e32 v59, v87
	v_mov_b32_e32 v60, v88
	v_mov_b32_e32 v61, v89
	v_mov_b32_e32 v62, v90
	v_mov_b32_e32 v63, v91
	v_lshlrev_b32_e32 v38, 16, v52
	v_lshlrev_b32_e32 v40, 16, v56
	v_and_b32_e32 v39, 0xffff0000, v52
	v_and_b32_e32 v41, 0xffff0000, v56
	v_lshlrev_b32_e32 v42, 16, v53
	v_lshlrev_b32_e32 v44, 16, v57
	v_and_b32_e32 v43, 0xffff0000, v53
	v_and_b32_e32 v45, 0xffff0000, v57
	v_lshlrev_b32_e32 v52, 16, v54
	v_lshlrev_b32_e32 v56, 16, v58
	v_and_b32_e32 v53, 0xffff0000, v54
	v_and_b32_e32 v57, 0xffff0000, v58
	v_lshlrev_b32_e32 v54, 16, v55
	v_lshlrev_b32_e32 v58, 16, v59
	v_and_b32_e32 v59, 0xffff0000, v59
	v_and_b32_e32 v55, 0xffff0000, v55
	v_pk_mul_f32 v[38:39], v[38:39], v[40:41]
	v_pk_mul_f32 v[40:41], v[42:43], v[44:45]
	v_pk_mul_f32 v[42:43], v[52:53], v[56:57]
	v_pk_mul_f32 v[44:45], v[54:55], v[58:59]
	v_lshlrev_b32_e32 v74, 16, v60
	v_and_b32_e32 v75, 0xffff0000, v60
	v_lshlrev_b32_e32 v60, 16, v61
	v_and_b32_e32 v61, 0xffff0000, v61
	v_lshlrev_b32_e32 v76, 16, v62
	v_and_b32_e32 v77, 0xffff0000, v62
	v_lshlrev_b32_e32 v62, 16, v63
	v_and_b32_e32 v63, 0xffff0000, v63
	v_pk_fma_f32 v[52:53], v[12:13], v[38:39], v[64:65]
	v_pk_fma_f32 v[54:55], v[14:15], v[40:41], v[66:67]
	v_pk_fma_f32 v[56:57], v[20:21], v[42:43], v[68:69]
	v_pk_fma_f32 v[58:59], v[22:23], v[44:45], v[70:71]
	v_pk_mul_f32 v[52:53], v[52:53], v[74:75]
	v_pk_mul_f32 v[54:55], v[54:55], v[60:61]
	v_pk_mul_f32 v[56:57], v[56:57], v[76:77]
	v_pk_mul_f32 v[58:59], v[58:59], v[62:63]
	v_cvt_pk_bf16_f32 v52, v52, v53
	v_cvt_pk_bf16_f32 v53, v54, v55
	v_cvt_pk_bf16_f32 v54, v56, v57
	v_cvt_pk_bf16_f32 v55, v58, v59
	global_store_dwordx4 v[72:73], v[52:55], off
	v_pk_mul_f32 v[64:65], v[8:9], v[38:39]
	v_pk_mul_f32 v[66:67], v[10:11], v[40:41]
	v_pk_mul_f32 v[68:69], v[16:17], v[42:43]
	v_pk_mul_f32 v[70:71], v[18:19], v[44:45]
	v_pk_fma_f32 v[64:65], v[4:5], v[26:27], v[64:65]
	v_pk_fma_f32 v[66:67], v[6:7], v[28:29], v[66:67]
	v_pk_fma_f32 v[68:69], v[0:1], v[30:31], v[68:69]
	v_pk_fma_f32 v[70:71], v[2:3], v[32:33], v[70:71]
	v_mov_b32_e32 v26, v38
	v_mov_b32_e32 v27, v39
	v_mov_b32_e32 v28, v40
	v_mov_b32_e32 v29, v41
	v_mov_b32_e32 v30, v42
	v_mov_b32_e32 v31, v43
	v_mov_b32_e32 v32, v44
	v_mov_b32_e32 v33, v45
	v_and_or_b32 v24, v49, s28, v47
	v_and_b32_e32 v51, 32, v50
	v_bitop3_b32 v24, v24, v48, v51 bitop3:0xde
	v_add_u32_e32 v50, 4, v50
	v_add_u32_e32 v49, 64, v49
	v_lshl_add_u64 v[72:73], v[34:35], 0, v[24:25]
	s_waitcnt vmcnt(2)
	v_mov_b32_e32 v52, v96
	v_mov_b32_e32 v53, v97
	v_mov_b32_e32 v54, v98
	v_mov_b32_e32 v55, v99
	v_mov_b32_e32 v56, v100
	v_mov_b32_e32 v57, v101
	v_mov_b32_e32 v58, v102
	v_mov_b32_e32 v59, v103
	v_mov_b32_e32 v60, v104
	v_mov_b32_e32 v61, v105
	v_mov_b32_e32 v62, v106
	v_mov_b32_e32 v63, v107
	v_lshlrev_b32_e32 v38, 16, v52
	v_lshlrev_b32_e32 v40, 16, v56
	v_and_b32_e32 v39, 0xffff0000, v52
	v_and_b32_e32 v41, 0xffff0000, v56
	v_lshlrev_b32_e32 v42, 16, v53
	v_lshlrev_b32_e32 v44, 16, v57
	v_and_b32_e32 v43, 0xffff0000, v53
	v_and_b32_e32 v45, 0xffff0000, v57
	v_lshlrev_b32_e32 v52, 16, v54
	v_lshlrev_b32_e32 v56, 16, v58
	v_and_b32_e32 v53, 0xffff0000, v54
	v_and_b32_e32 v57, 0xffff0000, v58
	v_lshlrev_b32_e32 v54, 16, v55
	v_lshlrev_b32_e32 v58, 16, v59
	v_and_b32_e32 v59, 0xffff0000, v59
	v_and_b32_e32 v55, 0xffff0000, v55
	v_pk_mul_f32 v[38:39], v[38:39], v[40:41]
	v_pk_mul_f32 v[40:41], v[42:43], v[44:45]
	v_pk_mul_f32 v[42:43], v[52:53], v[56:57]
	v_pk_mul_f32 v[44:45], v[54:55], v[58:59]
	v_lshlrev_b32_e32 v74, 16, v60
	v_and_b32_e32 v75, 0xffff0000, v60
	v_lshlrev_b32_e32 v60, 16, v61
	v_and_b32_e32 v61, 0xffff0000, v61
	v_lshlrev_b32_e32 v76, 16, v62
	v_and_b32_e32 v77, 0xffff0000, v62
	v_lshlrev_b32_e32 v62, 16, v63
	v_and_b32_e32 v63, 0xffff0000, v63
	v_pk_fma_f32 v[52:53], v[12:13], v[38:39], v[64:65]
	v_pk_fma_f32 v[54:55], v[14:15], v[40:41], v[66:67]
	v_pk_fma_f32 v[56:57], v[20:21], v[42:43], v[68:69]
	v_pk_fma_f32 v[58:59], v[22:23], v[44:45], v[70:71]
	v_pk_mul_f32 v[52:53], v[52:53], v[74:75]
	v_pk_mul_f32 v[54:55], v[54:55], v[60:61]
	v_pk_mul_f32 v[56:57], v[56:57], v[76:77]
	v_pk_mul_f32 v[58:59], v[58:59], v[62:63]
	v_cvt_pk_bf16_f32 v52, v52, v53
	v_cvt_pk_bf16_f32 v53, v54, v55
	v_cvt_pk_bf16_f32 v54, v56, v57
	v_cvt_pk_bf16_f32 v55, v58, v59
	global_store_dwordx4 v[72:73], v[52:55], off
	v_add_u32_e32 v160, s12, v160
	v_cmp_lt_i32_e32 vcc, s29, v160
	s_or_b64 s[2:3], vcc, s[2:3]
	v_add_u32_e32 v46, s13, v46
	s_andn2_b64 exec, exec, s[2:3]
	s_cbranch_execnz .LBB0_433
